# P4 SSM GEMM epilogue: uu/dsk loads prefetched (one wait per row group instead of one exposed round trip per fragment)
# speedup vs baseline: 1.0249x; 1.0119x over previous
; template <bool SWAP, class Epi>
; DI void gemm_tile(const u16* __restrict__ Ag, long lda, const u16* __restrict__ Bg, long ldb, int ka0, int ka1, int kb0, int kb1, char* shm, Epi&& epi) {
;     ...
;   for (int i = 0; i < nk; ++i) {
;     asm volatile("s_waitcnt vmcnt(0)" ::: "memory");
;     __syncthreads();
;     if (i + 1 < nk) { const int j = i + 1; stage(j & 1, j < na ? ka0 + j : kb0 + (j - na)); }
;     const char* SA = shm + (i & 1) * 32768; const char* SB = SA + 16384;
; #pragma unroll
;     for (int ks = 0; ks < 2; ++ks) {
;       bf16x8 At[4], Bt[4];
; #pragma unroll
;       for (int m = 0; m < 4; ++m) {
;         const int ra = wr * 64 + m * 16 + fr, rb = wc * 64 + m * 16 + fr;
;         At[m] = *reinterpret_cast<const bf16x8*>(SA + ra * 128 + (((ks * 4 + fq) ^ ((ra >> 1) & 7)) * 16));
;         Bt[m] = *reinterpret_cast<const bf16x8*>(SB + rb * 128 + (((ks * 4 + fq) ^ ((rb >> 1) & 7)) * 16));
;       }
; #pragma unroll
;       for (int m = 0; m < 4; ++m)
; #pragma unroll
;         for (int n = 0; n < 4; ++n) acc[m][n] = SWAP ? __builtin_amdgcn_mfma_f32_16x16x32_bf16(Bt[n], At[m], acc[m][n], 0, 0, 0) : __builtin_amdgcn_mfma_f32_16x16x32_bf16(At[m], Bt[n], acc[m][n], 0, 0, 0);
;     }
;   }
.LBB0_755:
	s_add_i32 s12, s5, 1
	v_add3_u32 v38, v37, s5, 17
	s_add_i32 s5, s4, 0x8000
	v_mov_b32_e32 v39, s12
	s_and_b32 s13, s5, 0x8000
	v_cmp_lt_u32_e32 vcc, s12, v36
	s_and_b32 s4, s4, 0x8000
	v_add_u32_e32 v116, s4, v192
	v_cndmask_b32_e32 v39, v38, v39, vcc
	v_add_u32_e32 v38, s13, v192
	v_lshlrev_b32_e32 v126, 6, v39
	v_add_u32_e32 v39, v38, v168
	v_add_u32_e32 v46, v38, v125
	v_add_u32_e32 v47, v38, v163
	v_lshlrev_b64 v[44:45], 1, v[126:127]
	v_readfirstlane_b32 s4, v39
	v_add_u32_e32 v39, 0x4000, v39
	v_add_u32_e32 v48, v38, v164
	v_readfirstlane_b32 s13, v46
	v_add_u32_e32 v58, 0x4000, v46
	v_readfirstlane_b32 s14, v47
	v_add_u32_e32 v62, 0x4000, v47
	v_lshl_add_u64 v[46:47], v[12:13], 0, v[44:45]
	v_readfirstlane_b32 s16, v39
	s_mov_b32 m0, s4
	s_waitcnt vmcnt(0)
	s_waitcnt vmcnt(0) lgkmcnt(0)
	s_barrier
	v_readfirstlane_b32 s15, v48
	v_add_u32_e32 v69, 0x4000, v48
	v_lshl_add_u64 v[48:49], v[14:15], 0, v[44:45]
	global_load_lds_dwordx4 v[46:47], off
	s_mov_b32 m0, s16
	v_lshl_add_u64 v[50:51], v[16:17], 0, v[44:45]
	v_readfirstlane_b32 s17, v58
	global_load_lds_dwordx4 v[48:49], off
	s_mov_b32 m0, s13
	v_lshl_add_u64 v[56:57], v[18:19], 0, v[44:45]
	global_load_lds_dwordx4 v[50:51], off
	s_mov_b32 m0, s17
	v_lshl_add_u64 v[58:59], v[24:25], 0, v[44:45]
	v_readfirstlane_b32 s20, v62
	global_load_lds_dwordx4 v[56:57], off
	s_mov_b32 m0, s14
	v_lshl_add_u64 v[60:61], v[26:27], 0, v[44:45]
	global_load_lds_dwordx4 v[58:59], off
	s_mov_b32 m0, s20
	v_lshl_add_u64 v[62:63], v[32:33], 0, v[44:45]
	v_readfirstlane_b32 s21, v69
	global_load_lds_dwordx4 v[60:61], off
	s_mov_b32 m0, s15
	v_lshl_add_u64 v[44:45], v[34:35], 0, v[44:45]
	global_load_lds_dwordx4 v[62:63], off
	s_mov_b32 m0, s21
	v_add_u32_e32 v117, v116, v166
	global_load_lds_dwordx4 v[44:45], off
	v_add_u32_e32 v92, v117, v172
	v_add_u32_e32 v39, v117, v177
	v_add_u32_e32 v68, v117, v167
	ds_read_b128 v[44:47], v92 offset:16384
	ds_read_b128 v[48:51], v68
	ds_read_b128 v[56:59], v92 offset:18432
	ds_read_b128 v[60:63], v92 offset:20480
	ds_read_b128 v[96:99], v39
	ds_read_b128 v[92:95], v92 offset:22528
	s_waitcnt lgkmcnt(0)
	v_mfma_f32_16x16x32_bf16 v[20:23], v[44:47], v[48:51], v[20:23]
	v_add_u32_e32 v39, v117, v179
	s_mov_b32 s4, s5
	s_mov_b32 s5, s12
	v_mfma_f32_16x16x32_bf16 v[68:71], v[56:59], v[48:51], v[112:115]
	v_mfma_f32_16x16x32_bf16 v[72:75], v[60:63], v[48:51], v[108:111]
	v_mfma_f32_16x16x32_bf16 v[48:51], v[92:95], v[48:51], v[104:107]
	s_nop 2
	v_add_u32_e32 v104, v117, v181
	v_mfma_f32_16x16x32_bf16 v[100:103], v[44:47], v[96:99], v[100:103]
	v_mfma_f32_16x16x32_bf16 v[88:91], v[56:59], v[96:99], v[88:91]
	v_mfma_f32_16x16x32_bf16 v[84:87], v[60:63], v[96:99], v[84:87]
	v_mfma_f32_16x16x32_bf16 v[80:83], v[92:95], v[96:99], v[80:83]
	ds_read_b128 v[96:99], v39
	ds_read_b128 v[104:107], v104
	v_add_u32_e32 v39, v116, v182
	s_waitcnt lgkmcnt(0)
	v_mfma_f32_16x16x32_bf16 v[76:79], v[44:47], v[96:99], v[76:79]
	v_mfma_f32_16x16x32_bf16 v[64:67], v[56:59], v[96:99], v[64:67]
	v_mfma_f32_16x16x32_bf16 v[52:55], v[60:63], v[96:99], v[52:55]
	v_mfma_f32_16x16x32_bf16 v[40:43], v[92:95], v[96:99], v[40:43]
	v_add_u32_e32 v96, v39, v172
	v_add_u32_e32 v97, v39, v177
	v_mfma_f32_16x16x32_bf16 v[8:11], v[56:59], v[104:107], v[8:11]
	v_add_u32_e32 v56, v39, v167
	v_mfma_f32_16x16x32_bf16 v[28:31], v[44:47], v[104:107], v[28:31]
	ds_read_b128 v[44:47], v96 offset:16384
	ds_read_b128 v[56:59], v56
	v_mfma_f32_16x16x32_bf16 v[4:7], v[60:63], v[104:107], v[4:7]
	ds_read_b128 v[60:63], v96 offset:18432
	v_mfma_f32_16x16x32_bf16 v[0:3], v[92:95], v[104:107], v[0:3]
	ds_read_b128 v[92:95], v96 offset:20480
	s_waitcnt lgkmcnt(0)
	v_mfma_f32_16x16x32_bf16 v[112:115], v[60:63], v[56:59], v[68:71]
	s_nop 2
	ds_read_b128 v[68:71], v96 offset:22528
	s_waitcnt lgkmcnt(0)
	v_mfma_f32_16x16x32_bf16 v[104:107], v[68:71], v[56:59], v[48:51]
	s_nop 2
	ds_read_b128 v[48:51], v97
	v_mfma_f32_16x16x32_bf16 v[20:23], v[44:47], v[56:59], v[20:23]
	v_mfma_f32_16x16x32_bf16 v[108:111], v[92:95], v[56:59], v[72:75]
	v_add_u32_e32 v56, v39, v179
	v_add_u32_e32 v39, v39, v181
	s_waitcnt lgkmcnt(0)
	v_mfma_f32_16x16x32_bf16 v[100:103], v[44:47], v[48:51], v[100:103]
	v_mfma_f32_16x16x32_bf16 v[88:91], v[60:63], v[48:51], v[88:91]
	v_mfma_f32_16x16x32_bf16 v[84:87], v[92:95], v[48:51], v[84:87]
	v_mfma_f32_16x16x32_bf16 v[80:83], v[68:71], v[48:51], v[80:83]
	ds_read_b128 v[48:51], v56
	ds_read_b128 v[56:59], v39
	v_add_u32_e32 v39, s12, v37
	v_cmp_eq_u32_e32 vcc, 1, v39
	s_waitcnt lgkmcnt(0)
	v_mfma_f32_16x16x32_bf16 v[76:79], v[44:47], v[48:51], v[76:79]
	s_or_b64 s[0:1], vcc, s[0:1]
	v_mfma_f32_16x16x32_bf16 v[64:67], v[60:63], v[48:51], v[64:67]
	v_mfma_f32_16x16x32_bf16 v[52:55], v[92:95], v[48:51], v[52:55]
	v_mfma_f32_16x16x32_bf16 v[40:43], v[68:71], v[48:51], v[40:43]
	v_mfma_f32_16x16x32_bf16 v[28:31], v[44:47], v[56:59], v[28:31]
	v_mfma_f32_16x16x32_bf16 v[8:11], v[60:63], v[56:59], v[8:11]
	v_mfma_f32_16x16x32_bf16 v[4:7], v[92:95], v[56:59], v[4:7]
	v_mfma_f32_16x16x32_bf16 v[0:3], v[68:71], v[56:59], v[0:3]
	s_andn2_b64 exec, exec, s[0:1]
	s_cbranch_execnz .LBB0_755
	s_or_b64 exec, exec, s[0:1]
	v_add_u32_e32 v12, v38, v166
	v_add_u32_e32 v13, v12, v167
	s_waitcnt vmcnt(0)
	s_waitcnt vmcnt(0)
	s_barrier
; DI unsigned pack2bf(float a, float b) { const f2_t v = {a, b}; return __builtin_bit_cast(unsigned, __builtin_convertvector(v, bf2_t)); }
; DI float gelu_t(float x) { float u = 0.7978845608028654f * (x + 0.044715f * x * x * x); float e = __expf(2.f * u); float t = 1.f - 2.f / (1.f + e); return 0.5f * x * (1.f + t); }
; template <bool SWAP, class Epi>
; DI void gemm_tile(const u16* __restrict__ Ag, long lda, const u16* __restrict__ Bg, long ldb, int ka0, int ka1, int kb0, int kb1, char* shm, Epi&& epi) {
;     ...
;       for (int m = 0; m < 4; ++m)
; #pragma unroll
;         for (int n = 0; n < 4; ++n) acc[m][n] = SWAP ? __builtin_amdgcn_mfma_f32_16x16x32_bf16(Bt[n], At[m], acc[m][n], 0, 0, 0) : __builtin_amdgcn_mfma_f32_16x16x32_bf16(At[m], Bt[n], acc[m][n], 0, 0, 0);
;     }
;   }
;   __syncthreads();
; #pragma unroll
;   for (int m = 0; m < 4; ++m)
; #pragma unroll
;     for (int n = 0; n < 4; ++n) { if (SWAP) epi(wr * 64 + m * 16 + fr, wc * 64 + n * 16 + fq * 4, acc[m][n]); else epi(wr * 64 + m * 16 + fq * 4, wc * 64 + n * 16 + fr, acc[m][n]); }
; DI void phase4(const Params& P, char* smem) {
;     ...
;       const int n = bcol + col0, i = n >> 4, h = n & 15, m = brow + row;
;       const float4 dsk = *reinterpret_cast<const float4*>(P.dsk + g * 16 + h);
;       const uint2 uu = *reinterpret_cast<const uint2*>(UG + ((long)g * 512 + m) * UGLD + n);
;       const float y0 = gelu_t(v[0] + dsk.x * __uint_as_float(uu.x << 16)), y1 = gelu_t(v[1] + dsk.y * __uint_as_float(uu.x & 0xffff0000u));
;       const float y2 = gelu_t(v[2] + dsk.z * __uint_as_float(uu.y << 16)), y3 = gelu_t(v[3] + dsk.w * __uint_as_float(uu.y & 0xffff0000u));
;       *reinterpret_cast<uint2*>(Yb + ((long)m * 64 + i) * 512 + g * 16 + h) = make_uint2(pack2bf(y0, y1), pack2bf(y2, y3));
	v_add_u32_e32 v16, v12, v172
	ds_read_b128 v[116:119], v13
	ds_read_b128 v[56:59], v16 offset:16384
	v_or_b32_e32 v220, v205, v165
	v_or_b32_e32 v126, v148, v220
	v_mov_b64_e32 v[154:155], s[18:19]
	s_waitcnt lgkmcnt(0)
	v_mfma_f32_16x16x32_bf16 v[210:213], v[56:59], v[116:119], v[20:23]
	v_or_b32_e32 v147, v183, v147
	v_mad_u64_u32 v[152:153], s[0:1], v126, s9, v[154:155]
	s_nop 0
	v_add_u32_e32 v20, v38, v182
	v_add_u32_e32 v17, v12, v177
	v_add_u32_e32 v13, v12, v179
	v_add_u32_e32 v12, v12, v181
	v_add_u32_e32 v21, v20, v167
	v_mad_i32_i24 v153, v149, s9, v153
	v_lshlrev_b32_e32 v126, 1, v147
	v_lshlrev_b32_e32 v218, 4, v150
	ds_read_b128 v[44:47], v16 offset:18432
	ds_read_b128 v[32:35], v16 offset:20480
	ds_read_b128 v[68:71], v13
	ds_read_b128 v[12:15], v12
	ds_read_b128 v[92:95], v17
	ds_read_b128 v[16:19], v16 offset:22528
	v_add_u32_e32 v24, v20, v172
	ds_read_b128 v[120:123], v21
	ds_read_b128 v[60:63], v24 offset:16384
	v_add_u32_e32 v25, v20, v177
	v_add_u32_e32 v21, v20, v179
	v_add_u32_e32 v20, v20, v181
	v_lshl_add_u64 v[158:159], v[152:153], 0, v[126:127]
	v_ashrrev_i32_e32 v219, 31, v218
	ds_read_b128 v[48:51], v24 offset:18432
	ds_read_b128 v[36:39], v24 offset:20480
	ds_read_b128 v[72:75], v21
	ds_read_b128 v[20:23], v20
	ds_read_b128 v[96:99], v25
	ds_read_b128 v[24:27], v24 offset:22528
	s_waitcnt lgkmcnt(0)
	s_barrier
	global_load_dwordx2 v[152:153], v[158:159], off
	v_lshl_add_u64 v[150:151], v[218:219], 2, v[130:131]
	global_load_dwordx4 v[214:217], v[150:151], off
	global_load_dwordx2 v[228:229], v[158:159], off offset:32
	global_load_dwordx2 v[230:231], v[158:159], off offset:64
	global_load_dwordx2 v[232:233], v[158:159], off offset:96
	v_or3_b32 v224, v148, v205, v176
	v_mad_u64_u32 v[224:225], s[0:1], v224, s9, v[154:155]
	v_mad_i32_i24 v225, v149, s9, v225
	v_lshl_add_u64 v[224:225], v[224:225], 0, v[126:127]
	global_load_dwordx2 v[234:235], v[224:225], off
	global_load_dwordx2 v[236:237], v[224:225], off offset:32
	global_load_dwordx2 v[238:239], v[224:225], off offset:64
	global_load_dwordx2 v[240:241], v[224:225], off offset:96
	v_or3_b32 v226, v148, v205, v178
	v_mad_u64_u32 v[226:227], s[0:1], v226, s9, v[154:155]
	v_mad_i32_i24 v227, v149, s9, v227
	v_lshl_add_u64 v[226:227], v[226:227], 0, v[126:127]
	global_load_dwordx2 v[242:243], v[226:227], off
	global_load_dwordx2 v[244:245], v[226:227], off offset:32
	global_load_dwordx2 v[246:247], v[226:227], off offset:64
	global_load_dwordx2 v[248:249], v[226:227], off offset:96
	v_mfma_f32_16x16x32_bf16 v[210:213], v[60:63], v[120:123], v[210:213]
	s_add_i32 s11, s11, s7
	s_cmpk_lt_i32 s11, 0x80
	s_waitcnt vmcnt(1)
	v_lshlrev_b32_e32 v156, 16, v152
	v_and_b32_e32 v157, 0xffff0000, v152
	s_waitcnt vmcnt(0)
	v_mov_b32_e32 v250, v214
	v_mov_b32_e32 v251, v215
	v_mov_b32_e32 v252, v216
	v_mov_b32_e32 v253, v217
	s_nop 1
	v_pk_fma_f32 v[156:157], v[214:215], v[156:157], v[210:211]
	v_lshlrev_b32_e32 v152, 16, v153
	v_mul_f32_e32 v160, 0x3d372713, v156
	v_mul_f32_e32 v161, 0x3d372713, v157
	v_mul_f32_e32 v160, v156, v160
	v_mul_f32_e32 v161, v157, v161
	v_fma_f32 v160, v156, v160, v156
	v_fma_f32 v161, v157, v161, v157
	v_mul_f32_e32 v160, 0x3f4c422a, v160
	v_mul_f32_e32 v161, 0x3f4c422a, v161
	v_add_f32_e32 v160, v160, v160
	v_add_f32_e32 v161, v161, v161
	v_mul_f32_e32 v160, 0x3fb8aa3b, v160
	v_mul_f32_e32 v161, 0x3fb8aa3b, v161
	v_exp_f32_e32 v160, v160
	v_exp_f32_e32 v161, v161
	v_and_b32_e32 v153, 0xffff0000, v153
	v_pk_fma_f32 v[152:153], v[216:217], v[152:153], v[212:213]
	v_pk_mul_f32 v[156:157], v[156:157], 0.5 op_sel_hi:[1,0]
	v_pk_add_f32 v[160:161], v[160:161], 1.0 op_sel_hi:[1,0]
	v_mul_f32_e32 v206, 0x3d372713, v152
	v_div_scale_f32 v210, s[0:1], v161, v161, 2.0
	v_div_scale_f32 v212, s[0:1], v160, v160, 2.0
	v_rcp_f32_e32 v213, v210
	v_mul_f32_e32 v207, 0x3d372713, v153
	v_rcp_f32_e32 v214, v212
	v_mul_f32_e32 v206, v152, v206
	v_mul_f32_e32 v207, v153, v207
	v_fma_f32 v206, v152, v206, v152
	v_fma_f32 v207, v153, v207, v153
	v_mul_f32_e32 v206, 0x3f4c422a, v206
	v_mul_f32_e32 v207, 0x3f4c422a, v207
	v_fma_f32 v216, -v210, v213, 1.0
	v_add_f32_e32 v206, v206, v206
	v_add_f32_e32 v207, v207, v207
	v_div_scale_f32 v211, vcc, 2.0, v161, 2.0
	v_fma_f32 v217, -v212, v214, 1.0
	v_fmac_f32_e32 v213, v216, v213
	v_mul_f32_e32 v206, 0x3fb8aa3b, v206
	v_mul_f32_e32 v207, 0x3fb8aa3b, v207
	v_div_scale_f32 v215, s[0:1], 2.0, v160, 2.0
	v_fmac_f32_e32 v214, v217, v214
	v_mul_f32_e32 v216, v211, v213
	v_exp_f32_e32 v206, v206
	v_exp_f32_e32 v207, v207
	v_mul_f32_e32 v217, v215, v214
	v_fma_f32 v221, -v210, v216, v211
	v_fma_f32 v222, -v212, v217, v215
	v_fmac_f32_e32 v216, v221, v213
	v_fmac_f32_e32 v217, v222, v214
	v_fma_f32 v210, -v210, v216, v211
	v_fma_f32 v211, -v212, v217, v215
	v_div_fmas_f32 v210, v210, v213, v216
	s_mov_b64 vcc, s[0:1]
	v_div_fixup_f32 v161, v210, v161, 2.0
	v_div_fmas_f32 v210, v211, v214, v217
	v_pk_add_f32 v[206:207], v[206:207], 1.0 op_sel_hi:[1,0]
	v_div_fixup_f32 v160, v210, v160, 2.0
	v_div_scale_f32 v210, s[0:1], v207, v207, 2.0
	v_rcp_f32_e32 v211, v210
	v_pk_add_f32 v[160:161], v[160:161], 1.0 op_sel_hi:[1,0] neg_lo:[1,0] neg_hi:[1,0]
	v_pk_mul_f32 v[152:153], v[152:153], 0.5 op_sel_hi:[1,0]
	v_pk_add_f32 v[160:161], v[160:161], 1.0 op_sel_hi:[1,0]
	v_mfma_f32_16x16x32_bf16 v[112:115], v[44:47], v[116:119], v[112:115]
	v_mul_f32_e64 v156, v156, v160
	v_mul_f32_e64 v157, v157, v161
	v_fma_f32 v160, -v210, v211, 1.0
	v_fmac_f32_e32 v211, v160, v211
	v_div_scale_f32 v160, vcc, 2.0, v207, 2.0
	v_mul_f32_e32 v161, v160, v211
	v_fma_f32 v212, -v210, v161, v160
	v_fmac_f32_e32 v161, v212, v211
	v_fma_f32 v160, -v210, v161, v160
; DI unsigned pack2bf(float a, float b) { const f2_t v = {a, b}; return __builtin_bit_cast(unsigned, __builtin_convertvector(v, bf2_t)); }
; DI float gelu_t(float x) { float u = 0.7978845608028654f * (x + 0.044715f * x * x * x); float e = __expf(2.f * u); float t = 1.f - 2.f / (1.f + e); return 0.5f * x * (1.f + t); }
; DI void phase4(const Params& P, char* smem) {
;     ...
;       const int n = bcol + col0, i = n >> 4, h = n & 15, m = brow + row;
;       const float4 dsk = *reinterpret_cast<const float4*>(P.dsk + g * 16 + h);
;       const uint2 uu = *reinterpret_cast<const uint2*>(UG + ((long)g * 512 + m) * UGLD + n);
;       const float y0 = gelu_t(v[0] + dsk.x * __uint_as_float(uu.x << 16)), y1 = gelu_t(v[1] + dsk.y * __uint_as_float(uu.x & 0xffff0000u));
;       const float y2 = gelu_t(v[2] + dsk.z * __uint_as_float(uu.y << 16)), y3 = gelu_t(v[3] + dsk.w * __uint_as_float(uu.y & 0xffff0000u));
;       *reinterpret_cast<uint2*>(Yb + ((long)m * 64 + i) * 512 + g * 16 + h) = make_uint2(pack2bf(y0, y1), pack2bf(y2, y3));
	v_div_scale_f32 v210, s[0:1], v206, v206, 2.0
	v_rcp_f32_e32 v212, v210
	v_div_fmas_f32 v160, v160, v211, v161
	v_div_fixup_f32 v161, v160, v207, 2.0
	v_mfma_f32_16x16x32_bf16 v[112:115], v[48:51], v[120:123], v[112:115]
	v_fma_f32 v160, -v210, v212, 1.0
	v_fmac_f32_e32 v212, v160, v212
	v_div_scale_f32 v160, vcc, 2.0, v206, 2.0
	v_mul_f32_e32 v207, v160, v212
	v_fma_f32 v211, -v210, v207, v160
	v_fmac_f32_e32 v207, v211, v212
	v_fma_f32 v160, -v210, v207, v160
	v_div_fmas_f32 v160, v160, v212, v207
	v_div_fixup_f32 v160, v160, v206, 2.0
	v_pk_add_f32 v[160:161], v[160:161], 1.0 op_sel_hi:[1,0] neg_lo:[1,0] neg_hi:[1,0]
	v_lshlrev_b32_e32 v206, 6, v147
	v_pk_add_f32 v[160:161], v[160:161], 1.0 op_sel_hi:[1,0]
	v_cvt_pk_bf16_f32 v210, v156, v157
	v_pk_mul_f32 v[152:153], v[152:153], v[160:161]
	v_and_b32_e32 v156, 0xf000, v206
	v_cvt_pk_bf16_f32 v211, v152, v153
	v_lshlrev_b32_e32 v152, 16, v220
	v_mov_b32_e32 v153, v127
	v_lshl_add_u64 v[160:161], s[54:55], 0, v[152:153]
	v_mov_b32_e32 v157, v127
	v_lshl_add_u64 v[212:213], v[160:161], 0, v[156:157]
	v_lshlrev_b64 v[152:153], 1, v[218:219]
	v_lshl_add_u64 v[212:213], v[212:213], 0, v[152:153]
	v_mov_b32_e32 v147, v127
	v_lshl_add_u64 v[212:213], v[212:213], 0, v[146:147]
	global_store_dwordx2 v[212:213], v[210:211], off
	v_mov_b32_e32 v214, v228
	v_mov_b32_e32 v215, v229
	v_mfma_f32_16x16x32_bf16 v[108:111], v[32:35], v[116:119], v[108:111]
	v_mov_b32_e32 v210, v250
	v_mov_b32_e32 v211, v251
	v_mov_b32_e32 v212, v252
	v_mov_b32_e32 v213, v253
	v_lshlrev_b32_e32 v216, 16, v214
	v_and_b32_e32 v217, 0xffff0000, v214
	v_pk_fma_f32 v[112:113], v[210:211], v[216:217], v[112:113]
	v_lshlrev_b32_e32 v214, 16, v215
	v_and_b32_e32 v215, 0xffff0000, v215
	v_mul_f32_e32 v207, 0x3d372713, v112
	v_mul_f32_e32 v210, 0x3d372713, v113
	v_pk_fma_f32 v[114:115], v[212:213], v[214:215], v[114:115]
	v_mul_f32_e32 v207, v112, v207
	v_mul_f32_e32 v210, v113, v210
	v_mul_f32_e32 v211, 0x3d372713, v114
	v_fma_f32 v207, v112, v207, v112
	v_fma_f32 v210, v113, v210, v113
	v_mul_f32_e32 v212, 0x3d372713, v115
	v_mul_f32_e32 v211, v114, v211
	v_mul_f32_e32 v207, 0x3f4c422a, v207
	v_mul_f32_e32 v210, 0x3f4c422a, v210
	v_mul_f32_e32 v212, v115, v212
	v_fma_f32 v211, v114, v211, v114
	v_add_f32_e32 v207, v207, v207
	v_add_f32_e32 v210, v210, v210
	v_fma_f32 v213, v115, v212, v115
	v_mul_f32_e32 v212, 0x3f4c422a, v211
	v_mul_f32_e32 v207, 0x3fb8aa3b, v207
	v_mul_f32_e32 v211, 0x3fb8aa3b, v210
	v_exp_f32_e32 v210, v207
	v_exp_f32_e32 v211, v211
	v_add_f32_e32 v207, v212, v212
	v_mul_f32_e32 v207, 0x3fb8aa3b, v207
	v_exp_f32_e32 v212, v207
	v_pk_add_f32 v[210:211], v[210:211], 1.0 op_sel_hi:[1,0]
	v_pk_mul_f32 v[112:113], v[112:113], 0.5 op_sel_hi:[1,0]
	v_div_scale_f32 v207, s[0:1], v211, v211, 2.0
	v_rcp_f32_e32 v216, v207
	v_div_scale_f32 v214, vcc, 2.0, v211, 2.0
	v_div_scale_f32 v215, s[0:1], v210, v210, 2.0
	v_fma_f32 v219, -v207, v216, 1.0
	v_fmac_f32_e32 v216, v219, v216
	v_mul_f32_e32 v219, v214, v216
	v_fma_f32 v221, -v207, v219, v214
	v_rcp_f32_e32 v217, v215
	v_fmac_f32_e32 v219, v221, v216
	v_fma_f32 v207, -v207, v219, v214
	v_div_fmas_f32 v207, v207, v216, v219
	v_div_fixup_f32 v211, v207, v211, 2.0
	v_mul_f32_e32 v207, 0x3f4c422a, v213
	v_fma_f32 v220, -v215, v217, 1.0
	v_add_f32_e32 v207, v207, v207
	v_div_scale_f32 v218, s[0:1], 2.0, v210, 2.0
	v_fmac_f32_e32 v217, v220, v217
	v_mul_f32_e32 v207, 0x3fb8aa3b, v207
	v_mul_f32_e32 v220, v218, v217
	v_exp_f32_e32 v213, v207
	v_fma_f32 v222, -v215, v220, v218
	v_fmac_f32_e32 v220, v222, v217
	v_fma_f32 v214, -v215, v220, v218
	s_mov_b64 vcc, s[0:1]
	v_div_fmas_f32 v207, v214, v217, v220
	v_pk_add_f32 v[212:213], v[212:213], 1.0 op_sel_hi:[1,0]
	v_div_fixup_f32 v210, v207, v210, 2.0
	v_div_scale_f32 v207, s[0:1], v213, v213, 2.0
	v_rcp_f32_e32 v214, v207
	v_pk_add_f32 v[210:211], v[210:211], 1.0 op_sel_hi:[1,0] neg_lo:[1,0] neg_hi:[1,0]
	v_pk_mul_f32 v[114:115], v[114:115], 0.5 op_sel_hi:[1,0]
	v_pk_add_f32 v[210:211], v[210:211], 1.0 op_sel_hi:[1,0]
	v_mfma_f32_16x16x32_bf16 v[108:111], v[36:39], v[120:123], v[108:111]
	v_mul_f32_e64 v112, v112, v210
	v_mul_f32_e64 v113, v113, v211
	v_fma_f32 v210, -v207, v214, 1.0
	v_fmac_f32_e32 v214, v210, v214
	v_div_scale_f32 v210, vcc, 2.0, v213, 2.0
	v_mul_f32_e32 v211, v210, v214
	v_fma_f32 v215, -v207, v211, v210
	v_fmac_f32_e32 v211, v215, v214
	v_fma_f32 v207, -v207, v211, v210
	v_div_scale_f32 v210, s[0:1], v212, v212, 2.0
	v_rcp_f32_e32 v215, v210
	v_div_fmas_f32 v207, v207, v214, v211
	v_div_fixup_f32 v211, v207, v213, 2.0
	v_mfma_f32_16x16x32_bf16 v[104:107], v[16:19], v[116:119], v[104:107]
	v_fma_f32 v207, -v210, v215, 1.0
	v_fmac_f32_e32 v215, v207, v215
	v_div_scale_f32 v207, vcc, 2.0, v212, 2.0
	v_mul_f32_e32 v213, v207, v215
	v_fma_f32 v214, -v210, v213, v207
	v_fmac_f32_e32 v213, v214, v215
	v_fma_f32 v207, -v210, v213, v207
	v_div_fmas_f32 v207, v207, v215, v213
	v_div_fixup_f32 v210, v207, v212, 2.0
	v_pk_add_f32 v[210:211], v[210:211], 1.0 op_sel_hi:[1,0] neg_lo:[1,0] neg_hi:[1,0]
	v_mfma_f32_16x16x32_bf16 v[104:107], v[24:27], v[120:123], v[104:107]
	v_add_f32_e64 v210, v210, 1.0
	v_add_f32_e64 v211, v211, 1.0
	v_pk_mul_f32 v[114:115], v[114:115], v[210:211]
	v_cvt_pk_bf16_f32 v210, v112, v113
	v_bitop3_b32 v112, v206, s10, v202 bitop3:0xc8
	v_mov_b32_e32 v113, v127
	v_cvt_pk_bf16_f32 v211, v114, v115
	v_lshl_add_u64 v[114:115], v[160:161], 0, v[112:113]
	v_lshl_add_u64 v[114:115], v[114:115], 0, v[152:153]
	v_lshl_add_u64 v[114:115], v[114:115], 0, v[146:147]
	global_store_dwordx2 v[114:115], v[210:211], off
	v_mov_b32_e32 v114, v230
	v_mov_b32_e32 v115, v231
	v_mfma_f32_16x16x32_bf16 v[100:103], v[56:59], v[92:95], v[100:103]
; DI unsigned pack2bf(float a, float b) { const f2_t v = {a, b}; return __builtin_bit_cast(unsigned, __builtin_convertvector(v, bf2_t)); }
; DI float gelu_t(float x) { float u = 0.7978845608028654f * (x + 0.044715f * x * x * x); float e = __expf(2.f * u); float t = 1.f - 2.f / (1.f + e); return 0.5f * x * (1.f + t); }
; DI void phase4(const Params& P, char* smem) {
;     ...
;       const int n = bcol + col0, i = n >> 4, h = n & 15, m = brow + row;
;       const float4 dsk = *reinterpret_cast<const float4*>(P.dsk + g * 16 + h);
;       const uint2 uu = *reinterpret_cast<const uint2*>(UG + ((long)g * 512 + m) * UGLD + n);
;       const float y0 = gelu_t(v[0] + dsk.x * __uint_as_float(uu.x << 16)), y1 = gelu_t(v[1] + dsk.y * __uint_as_float(uu.x & 0xffff0000u));
;       const float y2 = gelu_t(v[2] + dsk.z * __uint_as_float(uu.y << 16)), y3 = gelu_t(v[3] + dsk.w * __uint_as_float(uu.y & 0xffff0000u));
;       *reinterpret_cast<uint2*>(Yb + ((long)m * 64 + i) * 512 + g * 16 + h) = make_uint2(pack2bf(y0, y1), pack2bf(y2, y3));
	v_mov_b32_e32 v210, v250
	v_mov_b32_e32 v211, v251
	v_mov_b32_e32 v212, v252
	v_mov_b32_e32 v213, v253
	v_lshlrev_b32_e32 v214, 16, v114
	v_and_b32_e32 v215, 0xffff0000, v114
	v_lshlrev_b32_e32 v114, 16, v115
	v_and_b32_e32 v115, 0xffff0000, v115
	v_pk_fma_f32 v[108:109], v[210:211], v[214:215], v[108:109]
	v_pk_fma_f32 v[110:111], v[212:213], v[114:115], v[110:111]
	v_mul_f32_e32 v114, 0x3d372713, v108
	v_mul_f32_e32 v115, 0x3d372713, v109
	v_mul_f32_e32 v114, v108, v114
	v_mul_f32_e32 v115, v109, v115
	v_fma_f32 v114, v108, v114, v108
	v_fma_f32 v115, v109, v115, v109
	v_mul_f32_e32 v114, 0x3f4c422a, v114
	v_mul_f32_e32 v115, 0x3f4c422a, v115
	v_add_f32_e32 v114, v114, v114
	v_add_f32_e32 v115, v115, v115
	v_mul_f32_e32 v207, 0x3d372713, v110
	v_mul_f32_e32 v114, 0x3fb8aa3b, v114
	v_mul_f32_e32 v115, 0x3fb8aa3b, v115
	v_mul_f32_e32 v207, v110, v207
	v_exp_f32_e32 v114, v114
	v_exp_f32_e32 v115, v115
	v_mul_f32_e32 v210, 0x3d372713, v111
	v_fma_f32 v207, v110, v207, v110
	v_mul_f32_e32 v210, v111, v210
	v_mul_f32_e32 v207, 0x3f4c422a, v207
	v_fma_f32 v210, v111, v210, v111
	v_add_f32_e32 v207, v207, v207
	v_mul_f32_e32 v210, 0x3f4c422a, v210
	v_mul_f32_e32 v207, 0x3fb8aa3b, v207
	v_pk_add_f32 v[114:115], v[114:115], 1.0 op_sel_hi:[1,0]
	v_add_f32_e32 v211, v210, v210
	v_exp_f32_e32 v210, v207
	v_div_scale_f32 v207, s[0:1], v115, v115, 2.0
	v_rcp_f32_e32 v214, v207
	v_div_scale_f32 v212, vcc, 2.0, v115, 2.0
	v_div_scale_f32 v213, s[0:1], v114, v114, 2.0
	v_fma_f32 v217, -v207, v214, 1.0
	v_fmac_f32_e32 v214, v217, v214
	v_rcp_f32_e32 v215, v213
	v_mul_f32_e32 v217, v212, v214
	v_fma_f32 v219, -v207, v217, v212
	v_fmac_f32_e32 v217, v219, v214
	v_fma_f32 v207, -v207, v217, v212
	v_fma_f32 v218, -v213, v215, 1.0
	v_div_fmas_f32 v207, v207, v214, v217
	v_div_scale_f32 v216, s[0:1], 2.0, v114, 2.0
	v_fmac_f32_e32 v215, v218, v215
	v_div_fixup_f32 v115, v207, v115, 2.0
	v_mul_f32_e32 v207, 0x3fb8aa3b, v211
	v_mul_f32_e32 v218, v216, v215
	v_exp_f32_e32 v211, v207
	v_fma_f32 v220, -v213, v218, v216
	v_fmac_f32_e32 v218, v220, v215
	v_fma_f32 v212, -v213, v218, v216
	s_mov_b64 vcc, s[0:1]
	v_div_fmas_f32 v207, v212, v215, v218
	v_pk_add_f32 v[210:211], v[210:211], 1.0 op_sel_hi:[1,0]
	v_div_fixup_f32 v114, v207, v114, 2.0
	v_div_scale_f32 v207, s[0:1], v211, v211, 2.0
	v_rcp_f32_e32 v212, v207
	v_pk_add_f32 v[114:115], v[114:115], 1.0 op_sel_hi:[1,0] neg_lo:[1,0] neg_hi:[1,0]
	v_pk_mul_f32 v[108:109], v[108:109], 0.5 op_sel_hi:[1,0]
	v_pk_add_f32 v[114:115], v[114:115], 1.0 op_sel_hi:[1,0]
	v_pk_mul_f32 v[110:111], v[110:111], 0.5 op_sel_hi:[1,0]
	v_pk_mul_f32 v[108:109], v[108:109], v[114:115]
	v_fma_f32 v114, -v207, v212, 1.0
	v_fmac_f32_e32 v212, v114, v212
	v_div_scale_f32 v114, vcc, 2.0, v211, 2.0
	v_mul_f32_e32 v115, v114, v212
	v_fma_f32 v213, -v207, v115, v114
	v_fmac_f32_e32 v115, v213, v212
	v_fma_f32 v114, -v207, v115, v114
	v_div_scale_f32 v207, s[0:1], v210, v210, 2.0
	v_rcp_f32_e32 v213, v207
	v_div_fmas_f32 v114, v114, v212, v115
	v_div_fixup_f32 v115, v114, v211, 2.0
	v_mfma_f32_16x16x32_bf16 v[100:103], v[60:63], v[96:99], v[100:103]
	v_fma_f32 v114, -v207, v213, 1.0
	v_fmac_f32_e32 v213, v114, v213
	v_div_scale_f32 v114, vcc, 2.0, v210, 2.0
	v_mul_f32_e32 v211, v114, v213
	v_fma_f32 v212, -v207, v211, v114
	v_fmac_f32_e32 v211, v212, v213
	v_fma_f32 v114, -v207, v211, v114
	v_div_fmas_f32 v114, v114, v213, v211
	v_div_fixup_f32 v114, v114, v210, 2.0
	v_pk_add_f32 v[114:115], v[114:115], 1.0 op_sel_hi:[1,0] neg_lo:[1,0] neg_hi:[1,0]
	v_mfma_f32_16x16x32_bf16 v[88:91], v[44:47], v[92:95], v[88:91]
	v_add_f32_e64 v114, v114, 1.0
	v_add_f32_e64 v115, v115, 1.0
	v_pk_mul_f32 v[110:111], v[110:111], v[114:115]
	v_cvt_pk_bf16_f32 v114, v108, v109
	v_bitop3_b32 v108, v206, s10, v203 bitop3:0xc8
	v_mov_b32_e32 v109, v127
	v_cvt_pk_bf16_f32 v115, v110, v111
	v_lshl_add_u64 v[110:111], v[160:161], 0, v[108:109]
	v_lshl_add_u64 v[110:111], v[110:111], 0, v[152:153]
	v_lshl_add_u64 v[110:111], v[110:111], 0, v[146:147]
	global_store_dwordx2 v[110:111], v[114:115], off
	v_mov_b32_e32 v110, v232
	v_mov_b32_e32 v111, v233
	v_mfma_f32_16x16x32_bf16 v[88:91], v[48:51], v[96:99], v[88:91]
	v_mov_b32_e32 v114, v250
	v_mov_b32_e32 v115, v251
	v_mov_b32_e32 v116, v252
	v_mov_b32_e32 v117, v253
	v_lshlrev_b32_e32 v118, 16, v110
	v_and_b32_e32 v119, 0xffff0000, v110
	v_lshlrev_b32_e32 v110, 16, v111
	v_and_b32_e32 v111, 0xffff0000, v111
	v_pk_fma_f32 v[104:105], v[114:115], v[118:119], v[104:105]
	v_pk_fma_f32 v[106:107], v[116:117], v[110:111], v[106:107]
	v_mul_f32_e32 v110, 0x3d372713, v104
	v_mul_f32_e32 v111, 0x3d372713, v105
	v_mul_f32_e32 v110, v104, v110
	v_mul_f32_e32 v111, v105, v111
	v_fma_f32 v110, v104, v110, v104
	v_fma_f32 v111, v105, v111, v105
	v_mul_f32_e32 v110, 0x3f4c422a, v110
	v_mul_f32_e32 v111, 0x3f4c422a, v111
	v_add_f32_e32 v110, v110, v110
	v_add_f32_e32 v111, v111, v111
	v_mul_f32_e32 v110, 0x3fb8aa3b, v110
	v_mul_f32_e32 v111, 0x3fb8aa3b, v111
	v_exp_f32_e32 v110, v110
	v_exp_f32_e32 v111, v111
	v_mul_f32_e32 v114, 0x3d372713, v106
	v_mul_f32_e32 v115, 0x3d372713, v107
	v_mul_f32_e32 v114, v106, v114
	v_pk_add_f32 v[110:111], v[110:111], 1.0 op_sel_hi:[1,0]
	v_mul_f32_e32 v115, v107, v115
	v_div_scale_f32 v116, s[0:1], v111, v111, 2.0
	v_div_scale_f32 v118, s[0:1], v110, v110, 2.0
	v_rcp_f32_e32 v119, v116
	v_rcp_f32_e32 v120, v118
	v_fma_f32 v114, v106, v114, v106
	v_fma_f32 v115, v107, v115, v107
	v_mul_f32_e32 v114, 0x3f4c422a, v114
	v_mul_f32_e32 v115, 0x3f4c422a, v115
	v_fma_f32 v122, -v116, v119, 1.0
	v_add_f32_e32 v114, v114, v114
	v_add_f32_e32 v115, v115, v115
	v_div_scale_f32 v117, vcc, 2.0, v111, 2.0
; DI unsigned pack2bf(float a, float b) { const f2_t v = {a, b}; return __builtin_bit_cast(unsigned, __builtin_convertvector(v, bf2_t)); }
; DI float gelu_t(float x) { float u = 0.7978845608028654f * (x + 0.044715f * x * x * x); float e = __expf(2.f * u); float t = 1.f - 2.f / (1.f + e); return 0.5f * x * (1.f + t); }
; DI void phase4(const Params& P, char* smem) {
;     ...
;       const int n = bcol + col0, i = n >> 4, h = n & 15, m = brow + row;
;       const float4 dsk = *reinterpret_cast<const float4*>(P.dsk + g * 16 + h);
;       const uint2 uu = *reinterpret_cast<const uint2*>(UG + ((long)g * 512 + m) * UGLD + n);
;       const float y0 = gelu_t(v[0] + dsk.x * __uint_as_float(uu.x << 16)), y1 = gelu_t(v[1] + dsk.y * __uint_as_float(uu.x & 0xffff0000u));
;       const float y2 = gelu_t(v[2] + dsk.z * __uint_as_float(uu.y << 16)), y3 = gelu_t(v[3] + dsk.w * __uint_as_float(uu.y & 0xffff0000u));
;       *reinterpret_cast<uint2*>(Yb + ((long)m * 64 + i) * 512 + g * 16 + h) = make_uint2(pack2bf(y0, y1), pack2bf(y2, y3));
	v_fma_f32 v123, -v118, v120, 1.0
	v_fmac_f32_e32 v119, v122, v119
	v_mul_f32_e32 v114, 0x3fb8aa3b, v114
	v_mul_f32_e32 v115, 0x3fb8aa3b, v115
	v_div_scale_f32 v121, s[0:1], 2.0, v110, 2.0
	v_fmac_f32_e32 v120, v123, v120
	v_mul_f32_e32 v122, v117, v119
	v_exp_f32_e32 v114, v114
	v_exp_f32_e32 v115, v115
	v_mul_f32_e32 v123, v121, v120
	v_fma_f32 v158, -v116, v122, v117
	v_fma_f32 v159, -v118, v123, v121
	v_fmac_f32_e32 v122, v158, v119
	v_fmac_f32_e32 v123, v159, v120
	v_fma_f32 v116, -v116, v122, v117
	v_fma_f32 v117, -v118, v123, v121
	v_div_fmas_f32 v116, v116, v119, v122
	s_mov_b64 vcc, s[0:1]
	v_div_fixup_f32 v111, v116, v111, 2.0
	v_div_fmas_f32 v116, v117, v120, v123
	v_pk_add_f32 v[114:115], v[114:115], 1.0 op_sel_hi:[1,0]
	v_div_fixup_f32 v110, v116, v110, 2.0
	v_div_scale_f32 v116, s[0:1], v115, v115, 2.0
	v_rcp_f32_e32 v117, v116
	v_pk_add_f32 v[110:111], v[110:111], 1.0 op_sel_hi:[1,0] neg_lo:[1,0] neg_hi:[1,0]
	v_pk_mul_f32 v[104:105], v[104:105], 0.5 op_sel_hi:[1,0]
	v_pk_add_f32 v[110:111], v[110:111], 1.0 op_sel_hi:[1,0]
	v_pk_mul_f32 v[106:107], v[106:107], 0.5 op_sel_hi:[1,0]
	v_pk_mul_f32 v[104:105], v[104:105], v[110:111]
	v_fma_f32 v110, -v116, v117, 1.0
	v_fmac_f32_e32 v117, v110, v117
	v_div_scale_f32 v110, vcc, 2.0, v115, 2.0
	v_mul_f32_e32 v111, v110, v117
	v_fma_f32 v118, -v116, v111, v110
	v_fmac_f32_e32 v111, v118, v117
	v_fma_f32 v110, -v116, v111, v110
	v_div_scale_f32 v116, s[0:1], v114, v114, 2.0
	v_rcp_f32_e32 v118, v116
	v_div_fmas_f32 v110, v110, v117, v111
	v_div_fixup_f32 v111, v110, v115, 2.0
	v_or_b32_e32 v120, v205, v176
	v_fma_f32 v110, -v116, v118, 1.0
	v_fmac_f32_e32 v118, v110, v118
	v_div_scale_f32 v110, vcc, 2.0, v114, 2.0
	v_mul_f32_e32 v115, v110, v118
	v_fma_f32 v117, -v116, v115, v110
	v_fmac_f32_e32 v115, v117, v118
	v_fma_f32 v110, -v116, v115, v110
	v_div_fmas_f32 v110, v110, v118, v115
	v_div_fixup_f32 v110, v110, v114, 2.0
	v_pk_add_f32 v[110:111], v[110:111], 1.0 op_sel_hi:[1,0] neg_lo:[1,0] neg_hi:[1,0]
	v_mfma_f32_16x16x32_bf16 v[84:87], v[32:35], v[92:95], v[84:87]
	v_add_f32_e64 v110, v110, 1.0
	v_add_f32_e64 v111, v111, 1.0
	v_pk_mul_f32 v[106:107], v[106:107], v[110:111]
	v_cvt_pk_bf16_f32 v110, v104, v105
	v_bitop3_b32 v104, v206, s10, v204 bitop3:0xc8
	v_mov_b32_e32 v105, v127
	v_cvt_pk_bf16_f32 v111, v106, v107
	v_lshl_add_u64 v[106:107], v[160:161], 0, v[104:105]
	v_lshl_add_u64 v[106:107], v[106:107], 0, v[152:153]
	v_lshl_add_u64 v[106:107], v[106:107], 0, v[146:147]
	global_store_dwordx2 v[106:107], v[110:111], off
	v_or_b32_e32 v106, v148, v120
	v_mad_u64_u32 v[106:107], s[0:1], v106, s9, v[154:155]
	v_mad_i32_i24 v107, v149, s9, v107
	v_lshl_add_u64 v[106:107], v[106:107], 0, v[126:127]
	v_or3_b32 v224, v148, v205, v180
	v_mad_u64_u32 v[224:225], s[0:1], v224, s9, v[154:155]
	v_mad_i32_i24 v225, v149, s9, v225
	v_lshl_add_u64 v[224:225], v[224:225], 0, v[126:127]
	global_load_dwordx2 v[228:229], v[224:225], off
	global_load_dwordx2 v[230:231], v[224:225], off offset:32
	global_load_dwordx2 v[232:233], v[224:225], off offset:64
	global_load_dwordx2 v[226:227], v[224:225], off offset:96
	v_mov_b32_e32 v110, v234
	v_mov_b32_e32 v111, v235
	v_mov_b32_e32 v114, v250
	v_mov_b32_e32 v115, v251
	v_mov_b32_e32 v116, v252
	v_mov_b32_e32 v117, v253
	v_mfma_f32_16x16x32_bf16 v[84:87], v[36:39], v[96:99], v[84:87]
	v_lshlrev_b32_e32 v118, 16, v110
	v_and_b32_e32 v119, 0xffff0000, v110
	v_lshlrev_b32_e32 v110, 16, v111
	v_and_b32_e32 v111, 0xffff0000, v111
	v_pk_fma_f32 v[100:101], v[114:115], v[118:119], v[100:101]
	v_pk_fma_f32 v[102:103], v[116:117], v[110:111], v[102:103]
	v_mul_f32_e32 v110, 0x3d372713, v100
	v_mul_f32_e32 v111, 0x3d372713, v101
	v_mul_f32_e32 v110, v100, v110
	v_mul_f32_e32 v111, v101, v111
	v_fma_f32 v110, v100, v110, v100
	v_fma_f32 v111, v101, v111, v101
	v_mul_f32_e32 v110, 0x3f4c422a, v110
	v_mul_f32_e32 v111, 0x3f4c422a, v111
	v_add_f32_e32 v110, v110, v110
	v_add_f32_e32 v111, v111, v111
	v_mul_f32_e32 v110, 0x3fb8aa3b, v110
	v_mul_f32_e32 v111, 0x3fb8aa3b, v111
	v_exp_f32_e32 v110, v110
	v_exp_f32_e32 v111, v111
	v_mul_f32_e32 v114, 0x3d372713, v102
	v_mul_f32_e32 v115, 0x3d372713, v103
	v_mul_f32_e32 v114, v102, v114
	v_pk_add_f32 v[110:111], v[110:111], 1.0 op_sel_hi:[1,0]
	v_mul_f32_e32 v115, v103, v115
	v_div_scale_f32 v116, s[0:1], v111, v111, 2.0
	v_div_scale_f32 v118, s[0:1], v110, v110, 2.0
	v_rcp_f32_e32 v119, v116
	v_rcp_f32_e32 v121, v118
	v_fma_f32 v114, v102, v114, v102
	v_fma_f32 v115, v103, v115, v103
	v_mul_f32_e32 v114, 0x3f4c422a, v114
	v_fma_f32 v123, -v116, v119, 1.0
	v_mul_f32_e32 v115, 0x3f4c422a, v115
	v_add_f32_e32 v114, v114, v114
	v_div_scale_f32 v117, vcc, 2.0, v111, 2.0
	v_fma_f32 v158, -v118, v121, 1.0
	v_fmac_f32_e32 v119, v123, v119
	v_add_f32_e32 v115, v115, v115
	v_mul_f32_e32 v114, 0x3fb8aa3b, v114
	v_div_scale_f32 v122, s[0:1], 2.0, v110, 2.0
	v_fmac_f32_e32 v121, v158, v121
	v_mul_f32_e32 v123, v117, v119
	v_mul_f32_e32 v115, 0x3fb8aa3b, v115
	v_exp_f32_e32 v114, v114
	v_mul_f32_e32 v158, v122, v121
	v_fma_f32 v159, -v116, v123, v117
	v_exp_f32_e32 v115, v115
	v_fma_f32 v160, -v118, v158, v122
	v_fmac_f32_e32 v123, v159, v119
	v_fmac_f32_e32 v158, v160, v121
	v_fma_f32 v116, -v116, v123, v117
	v_fma_f32 v117, -v118, v158, v122
	v_div_fmas_f32 v116, v116, v119, v123
	s_mov_b64 vcc, s[0:1]
	v_div_fixup_f32 v111, v116, v111, 2.0
	v_div_fmas_f32 v116, v117, v121, v158
	v_pk_add_f32 v[114:115], v[114:115], 1.0 op_sel_hi:[1,0]
	v_div_fixup_f32 v110, v116, v110, 2.0
	v_div_scale_f32 v116, s[0:1], v115, v115, 2.0
	v_rcp_f32_e32 v117, v116
	v_pk_add_f32 v[110:111], v[110:111], 1.0 op_sel_hi:[1,0] neg_lo:[1,0] neg_hi:[1,0]
; DI unsigned pack2bf(float a, float b) { const f2_t v = {a, b}; return __builtin_bit_cast(unsigned, __builtin_convertvector(v, bf2_t)); }
; DI float gelu_t(float x) { float u = 0.7978845608028654f * (x + 0.044715f * x * x * x); float e = __expf(2.f * u); float t = 1.f - 2.f / (1.f + e); return 0.5f * x * (1.f + t); }
; DI void phase4(const Params& P, char* smem) {
;     ...
;       const int n = bcol + col0, i = n >> 4, h = n & 15, m = brow + row;
;       const float4 dsk = *reinterpret_cast<const float4*>(P.dsk + g * 16 + h);
;       const uint2 uu = *reinterpret_cast<const uint2*>(UG + ((long)g * 512 + m) * UGLD + n);
;       const float y0 = gelu_t(v[0] + dsk.x * __uint_as_float(uu.x << 16)), y1 = gelu_t(v[1] + dsk.y * __uint_as_float(uu.x & 0xffff0000u));
;       const float y2 = gelu_t(v[2] + dsk.z * __uint_as_float(uu.y << 16)), y3 = gelu_t(v[3] + dsk.w * __uint_as_float(uu.y & 0xffff0000u));
;       *reinterpret_cast<uint2*>(Yb + ((long)m * 64 + i) * 512 + g * 16 + h) = make_uint2(pack2bf(y0, y1), pack2bf(y2, y3));
	v_pk_mul_f32 v[100:101], v[100:101], 0.5 op_sel_hi:[1,0]
	v_pk_add_f32 v[110:111], v[110:111], 1.0 op_sel_hi:[1,0]
	v_pk_mul_f32 v[102:103], v[102:103], 0.5 op_sel_hi:[1,0]
	v_pk_mul_f32 v[100:101], v[100:101], v[110:111]
	v_fma_f32 v110, -v116, v117, 1.0
	v_fmac_f32_e32 v117, v110, v117
	v_div_scale_f32 v110, vcc, 2.0, v115, 2.0
	v_mul_f32_e32 v111, v110, v117
	v_fma_f32 v118, -v116, v111, v110
	v_fmac_f32_e32 v111, v118, v117
	v_fma_f32 v110, -v116, v111, v110
	v_div_scale_f32 v116, s[0:1], v114, v114, 2.0
	v_rcp_f32_e32 v118, v116
	v_div_fmas_f32 v110, v110, v117, v111
	v_div_fixup_f32 v111, v110, v115, 2.0
	v_mfma_f32_16x16x32_bf16 v[80:83], v[16:19], v[92:95], v[80:83]
	v_fma_f32 v110, -v116, v118, 1.0
	v_fmac_f32_e32 v118, v110, v118
	v_div_scale_f32 v110, vcc, 2.0, v114, 2.0
	v_mul_f32_e32 v115, v110, v118
	v_fma_f32 v117, -v116, v115, v110
	v_fmac_f32_e32 v115, v117, v118
	v_fma_f32 v110, -v116, v115, v110
	v_div_fmas_f32 v110, v110, v118, v115
	v_div_fixup_f32 v110, v110, v114, 2.0
	v_pk_add_f32 v[110:111], v[110:111], 1.0 op_sel_hi:[1,0] neg_lo:[1,0] neg_hi:[1,0]
	v_mfma_f32_16x16x32_bf16 v[80:83], v[24:27], v[96:99], v[80:83]
	v_add_f32_e64 v110, v110, 1.0
	v_add_f32_e64 v111, v111, 1.0
	v_pk_mul_f32 v[102:103], v[102:103], v[110:111]
	v_cvt_pk_bf16_f32 v110, v100, v101
	v_lshlrev_b32_e32 v100, 16, v120
	v_mov_b32_e32 v101, v127
	v_lshl_add_u64 v[100:101], s[54:55], 0, v[100:101]
	v_cvt_pk_bf16_f32 v111, v102, v103
	v_lshl_add_u64 v[102:103], v[100:101], 0, v[156:157]
	v_lshl_add_u64 v[102:103], v[102:103], 0, v[152:153]
	v_lshl_add_u64 v[102:103], v[102:103], 0, v[146:147]
	global_store_dwordx2 v[102:103], v[110:111], off
	v_mov_b32_e32 v102, v236
	v_mov_b32_e32 v103, v237
	v_mfma_f32_16x16x32_bf16 v[76:79], v[56:59], v[68:71], v[76:79]
	v_mov_b32_e32 v114, v250
	v_mov_b32_e32 v115, v251
	v_mov_b32_e32 v116, v252
	v_mov_b32_e32 v117, v253
	v_lshlrev_b32_e32 v110, 16, v102
	v_and_b32_e32 v111, 0xffff0000, v102
	v_lshlrev_b32_e32 v102, 16, v103
	v_and_b32_e32 v103, 0xffff0000, v103
	v_pk_fma_f32 v[88:89], v[114:115], v[110:111], v[88:89]
	v_pk_fma_f32 v[90:91], v[116:117], v[102:103], v[90:91]
	v_mul_f32_e32 v102, 0x3d372713, v88
	v_mul_f32_e32 v103, 0x3d372713, v89
	v_mul_f32_e32 v102, v88, v102
	v_mul_f32_e32 v103, v89, v103
	v_fma_f32 v102, v88, v102, v88
	v_fma_f32 v103, v89, v103, v89
	v_mul_f32_e32 v102, 0x3f4c422a, v102
	v_mul_f32_e32 v103, 0x3f4c422a, v103
	v_add_f32_e32 v102, v102, v102
	v_add_f32_e32 v103, v103, v103
	v_mul_f32_e32 v102, 0x3fb8aa3b, v102
	v_mul_f32_e32 v103, 0x3fb8aa3b, v103
	v_exp_f32_e32 v102, v102
	v_exp_f32_e32 v103, v103
	v_mul_f32_e32 v110, 0x3d372713, v90
	v_mul_f32_e32 v111, 0x3d372713, v91
	v_mul_f32_e32 v110, v90, v110
	v_pk_add_f32 v[102:103], v[102:103], 1.0 op_sel_hi:[1,0]
	v_mul_f32_e32 v111, v91, v111
	v_div_scale_f32 v114, s[0:1], v103, v103, 2.0
	v_div_scale_f32 v116, s[0:1], v102, v102, 2.0
	v_rcp_f32_e32 v117, v114
	v_rcp_f32_e32 v118, v116
	v_fma_f32 v110, v90, v110, v90
	v_fma_f32 v111, v91, v111, v91
	v_mul_f32_e32 v110, 0x3f4c422a, v110
	v_mul_f32_e32 v111, 0x3f4c422a, v111
	v_fma_f32 v120, -v114, v117, 1.0
	v_add_f32_e32 v110, v110, v110
	v_div_scale_f32 v115, vcc, 2.0, v103, 2.0
	v_fma_f32 v121, -v116, v118, 1.0
	v_fmac_f32_e32 v117, v120, v117
	v_add_f32_e32 v111, v111, v111
	v_mul_f32_e32 v110, 0x3fb8aa3b, v110
	v_div_scale_f32 v119, s[0:1], 2.0, v102, 2.0
	v_fmac_f32_e32 v118, v121, v118
	v_mul_f32_e32 v120, v115, v117
	v_mul_f32_e32 v111, 0x3fb8aa3b, v111
	v_exp_f32_e32 v110, v110
	v_mul_f32_e32 v121, v119, v118
	v_fma_f32 v122, -v114, v120, v115
	v_exp_f32_e32 v111, v111
	v_fma_f32 v123, -v116, v121, v119
	v_fmac_f32_e32 v120, v122, v117
	v_fmac_f32_e32 v121, v123, v118
	v_fma_f32 v114, -v114, v120, v115
	v_fma_f32 v115, -v116, v121, v119
	v_div_fmas_f32 v114, v114, v117, v120
	s_mov_b64 vcc, s[0:1]
	v_div_fixup_f32 v103, v114, v103, 2.0
	v_div_fmas_f32 v114, v115, v118, v121
	v_pk_add_f32 v[110:111], v[110:111], 1.0 op_sel_hi:[1,0]
	v_div_fixup_f32 v102, v114, v102, 2.0
	v_div_scale_f32 v114, s[0:1], v111, v111, 2.0
	v_rcp_f32_e32 v115, v114
	v_pk_add_f32 v[102:103], v[102:103], 1.0 op_sel_hi:[1,0] neg_lo:[1,0] neg_hi:[1,0]
	v_pk_mul_f32 v[88:89], v[88:89], 0.5 op_sel_hi:[1,0]
	v_pk_add_f32 v[102:103], v[102:103], 1.0 op_sel_hi:[1,0]
	v_pk_mul_f32 v[90:91], v[90:91], 0.5 op_sel_hi:[1,0]
	v_pk_mul_f32 v[88:89], v[88:89], v[102:103]
	v_fma_f32 v102, -v114, v115, 1.0
	v_fmac_f32_e32 v115, v102, v115
	v_div_scale_f32 v102, vcc, 2.0, v111, 2.0
	v_mul_f32_e32 v103, v102, v115
	v_fma_f32 v116, -v114, v103, v102
	v_fmac_f32_e32 v103, v116, v115
	v_fma_f32 v102, -v114, v103, v102
	v_div_scale_f32 v114, s[0:1], v110, v110, 2.0
	v_rcp_f32_e32 v116, v114
	v_div_fmas_f32 v102, v102, v115, v103
	v_div_fixup_f32 v103, v102, v111, 2.0
	v_cvt_pk_bf16_f32 v88, v88, v89
	v_fma_f32 v102, -v114, v116, 1.0
	v_fmac_f32_e32 v116, v102, v116
	v_div_scale_f32 v102, vcc, 2.0, v110, 2.0
	v_mul_f32_e32 v111, v102, v116
	v_fma_f32 v115, -v114, v111, v102
	v_fmac_f32_e32 v111, v115, v116
	v_fma_f32 v102, -v114, v111, v102
	v_div_fmas_f32 v102, v102, v116, v111
	v_div_fixup_f32 v102, v102, v110, 2.0
	v_pk_add_f32 v[102:103], v[102:103], 1.0 op_sel_hi:[1,0] neg_lo:[1,0] neg_hi:[1,0]
	v_mfma_f32_16x16x32_bf16 v[76:79], v[60:63], v[72:75], v[76:79]
	v_add_f32_e64 v102, v102, 1.0
	v_add_f32_e64 v103, v103, 1.0
	v_pk_mul_f32 v[90:91], v[90:91], v[102:103]
	v_mfma_f32_16x16x32_bf16 v[64:67], v[44:47], v[68:71], v[64:67]
	v_cvt_pk_bf16_f32 v89, v90, v91
	v_lshl_add_u64 v[90:91], v[100:101], 0, v[112:113]
	v_lshl_add_u64 v[90:91], v[90:91], 0, v[152:153]
	v_lshl_add_u64 v[90:91], v[90:91], 0, v[146:147]
; DI unsigned pack2bf(float a, float b) { const f2_t v = {a, b}; return __builtin_bit_cast(unsigned, __builtin_convertvector(v, bf2_t)); }
; DI float gelu_t(float x) { float u = 0.7978845608028654f * (x + 0.044715f * x * x * x); float e = __expf(2.f * u); float t = 1.f - 2.f / (1.f + e); return 0.5f * x * (1.f + t); }
; DI void phase4(const Params& P, char* smem) {
;     ...
;       const int n = bcol + col0, i = n >> 4, h = n & 15, m = brow + row;
;       const float4 dsk = *reinterpret_cast<const float4*>(P.dsk + g * 16 + h);
;       const uint2 uu = *reinterpret_cast<const uint2*>(UG + ((long)g * 512 + m) * UGLD + n);
;       const float y0 = gelu_t(v[0] + dsk.x * __uint_as_float(uu.x << 16)), y1 = gelu_t(v[1] + dsk.y * __uint_as_float(uu.x & 0xffff0000u));
;       const float y2 = gelu_t(v[2] + dsk.z * __uint_as_float(uu.y << 16)), y3 = gelu_t(v[3] + dsk.w * __uint_as_float(uu.y & 0xffff0000u));
;       *reinterpret_cast<uint2*>(Yb + ((long)m * 64 + i) * 512 + g * 16 + h) = make_uint2(pack2bf(y0, y1), pack2bf(y2, y3));
	global_store_dwordx2 v[90:91], v[88:89], off
	v_mov_b32_e32 v102, v238
	v_mov_b32_e32 v103, v239
	v_mfma_f32_16x16x32_bf16 v[64:67], v[48:51], v[72:75], v[64:67]
	v_mov_b32_e32 v88, v250
	v_mov_b32_e32 v89, v251
	v_mov_b32_e32 v90, v252
	v_mov_b32_e32 v91, v253
	v_lshlrev_b32_e32 v110, 16, v102
	v_and_b32_e32 v111, 0xffff0000, v102
	v_pk_fma_f32 v[84:85], v[88:89], v[110:111], v[84:85]
	v_lshlrev_b32_e32 v102, 16, v103
	v_mul_f32_e32 v88, 0x3d372713, v84
	v_mul_f32_e32 v89, 0x3d372713, v85
	v_mul_f32_e32 v88, v84, v88
	v_mul_f32_e32 v89, v85, v89
	v_fma_f32 v88, v84, v88, v84
	v_fma_f32 v89, v85, v89, v85
	v_mul_f32_e32 v88, 0x3f4c422a, v88
	v_mul_f32_e32 v89, 0x3f4c422a, v89
	v_add_f32_e32 v88, v88, v88
	v_add_f32_e32 v89, v89, v89
	v_mul_f32_e32 v88, 0x3fb8aa3b, v88
	v_mul_f32_e32 v89, 0x3fb8aa3b, v89
	v_exp_f32_e32 v88, v88
	v_exp_f32_e32 v89, v89
	v_and_b32_e32 v103, 0xffff0000, v103
	v_pk_fma_f32 v[86:87], v[90:91], v[102:103], v[86:87]
	v_pk_mul_f32 v[84:85], v[84:85], 0.5 op_sel_hi:[1,0]
	v_pk_add_f32 v[88:89], v[88:89], 1.0 op_sel_hi:[1,0]
	v_mul_f32_e32 v90, 0x3d372713, v86
	v_div_scale_f32 v102, s[0:1], v89, v89, 2.0
	v_div_scale_f32 v110, s[0:1], v88, v88, 2.0
	v_rcp_f32_e32 v111, v102
	v_mul_f32_e32 v91, 0x3d372713, v87
	v_rcp_f32_e32 v114, v110
	v_mul_f32_e32 v90, v86, v90
	v_mul_f32_e32 v91, v87, v91
	v_fma_f32 v90, v86, v90, v86
	v_fma_f32 v91, v87, v91, v87
	v_mul_f32_e32 v90, 0x3f4c422a, v90
	v_mul_f32_e32 v91, 0x3f4c422a, v91
	v_fma_f32 v116, -v102, v111, 1.0
	v_add_f32_e32 v90, v90, v90
	v_add_f32_e32 v91, v91, v91
	v_div_scale_f32 v103, vcc, 2.0, v89, 2.0
	v_fma_f32 v117, -v110, v114, 1.0
	v_fmac_f32_e32 v111, v116, v111
	v_mul_f32_e32 v90, 0x3fb8aa3b, v90
	v_mul_f32_e32 v91, 0x3fb8aa3b, v91
	v_div_scale_f32 v115, s[0:1], 2.0, v88, 2.0
	v_fmac_f32_e32 v114, v117, v114
	v_mul_f32_e32 v116, v103, v111
	v_exp_f32_e32 v90, v90
	v_exp_f32_e32 v91, v91
	v_mul_f32_e32 v117, v115, v114
	v_fma_f32 v118, -v102, v116, v103
	v_fma_f32 v119, -v110, v117, v115
	v_fmac_f32_e32 v116, v118, v111
	v_fmac_f32_e32 v117, v119, v114
	v_fma_f32 v102, -v102, v116, v103
	v_fma_f32 v103, -v110, v117, v115
	v_div_fmas_f32 v102, v102, v111, v116
	s_mov_b64 vcc, s[0:1]
	v_div_fixup_f32 v89, v102, v89, 2.0
	v_div_fmas_f32 v102, v103, v114, v117
	v_pk_add_f32 v[90:91], v[90:91], 1.0 op_sel_hi:[1,0]
	v_div_fixup_f32 v88, v102, v88, 2.0
	v_div_scale_f32 v102, s[0:1], v91, v91, 2.0
	v_rcp_f32_e32 v103, v102
	v_pk_add_f32 v[88:89], v[88:89], 1.0 op_sel_hi:[1,0] neg_lo:[1,0] neg_hi:[1,0]
	v_pk_mul_f32 v[86:87], v[86:87], 0.5 op_sel_hi:[1,0]
	v_pk_add_f32 v[88:89], v[88:89], 1.0 op_sel_hi:[1,0]
	v_mfma_f32_16x16x32_bf16 v[52:55], v[32:35], v[68:71], v[52:55]
	v_mul_f32_e64 v84, v84, v88
	v_mul_f32_e64 v85, v85, v89
	v_fma_f32 v88, -v102, v103, 1.0
	v_fmac_f32_e32 v103, v88, v103
	v_div_scale_f32 v88, vcc, 2.0, v91, 2.0
	v_mul_f32_e32 v89, v88, v103
	v_fma_f32 v110, -v102, v89, v88
	v_fmac_f32_e32 v89, v110, v103
	v_fma_f32 v88, -v102, v89, v88
	v_div_scale_f32 v102, s[0:1], v90, v90, 2.0
	v_rcp_f32_e32 v110, v102
	v_div_fmas_f32 v88, v88, v103, v89
	v_div_fixup_f32 v89, v88, v91, 2.0
	v_cvt_pk_bf16_f32 v84, v84, v85
	v_fma_f32 v88, -v102, v110, 1.0
	v_fmac_f32_e32 v110, v88, v110
	v_div_scale_f32 v88, vcc, 2.0, v90, 2.0
	v_mul_f32_e32 v91, v88, v110
	v_fma_f32 v103, -v102, v91, v88
	v_fmac_f32_e32 v91, v103, v110
	v_fma_f32 v88, -v102, v91, v88
	v_div_fmas_f32 v88, v88, v110, v91
	v_div_fixup_f32 v88, v88, v90, 2.0
	v_pk_add_f32 v[88:89], v[88:89], 1.0 op_sel_hi:[1,0] neg_lo:[1,0] neg_hi:[1,0]
	v_mfma_f32_16x16x32_bf16 v[52:55], v[36:39], v[72:75], v[52:55]
	v_add_f32_e64 v88, v88, 1.0
	v_add_f32_e64 v89, v89, 1.0
	v_pk_mul_f32 v[86:87], v[86:87], v[88:89]
	v_mfma_f32_16x16x32_bf16 v[40:43], v[16:19], v[68:71], v[40:43]
	v_cvt_pk_bf16_f32 v85, v86, v87
	v_lshl_add_u64 v[86:87], v[100:101], 0, v[108:109]
	v_lshl_add_u64 v[86:87], v[86:87], 0, v[152:153]
	v_lshl_add_u64 v[86:87], v[86:87], 0, v[146:147]
	global_store_dwordx2 v[86:87], v[84:85], off
	v_mov_b32_e32 v88, v240
	v_mov_b32_e32 v89, v241
	v_mfma_f32_16x16x32_bf16 v[40:43], v[24:27], v[72:75], v[40:43]
	v_mov_b32_e32 v84, v250
	v_mov_b32_e32 v85, v251
	v_mov_b32_e32 v86, v252
	v_mov_b32_e32 v87, v253
	v_lshlrev_b32_e32 v90, 16, v88
	v_and_b32_e32 v91, 0xffff0000, v88
	v_pk_fma_f32 v[80:81], v[84:85], v[90:91], v[80:81]
	v_lshlrev_b32_e32 v88, 16, v89
	v_mul_f32_e32 v84, 0x3d372713, v80
	v_mul_f32_e32 v85, 0x3d372713, v81
	v_mul_f32_e32 v84, v80, v84
	v_mul_f32_e32 v85, v81, v85
	v_fma_f32 v84, v80, v84, v80
	v_fma_f32 v85, v81, v85, v81
	v_mul_f32_e32 v84, 0x3f4c422a, v84
	v_mul_f32_e32 v85, 0x3f4c422a, v85
	v_add_f32_e32 v84, v84, v84
	v_add_f32_e32 v85, v85, v85
	v_mul_f32_e32 v84, 0x3fb8aa3b, v84
	v_mul_f32_e32 v85, 0x3fb8aa3b, v85
	v_exp_f32_e32 v84, v84
	v_exp_f32_e32 v85, v85
	v_and_b32_e32 v89, 0xffff0000, v89
	v_pk_fma_f32 v[82:83], v[86:87], v[88:89], v[82:83]
	v_pk_mul_f32 v[80:81], v[80:81], 0.5 op_sel_hi:[1,0]
	v_pk_add_f32 v[84:85], v[84:85], 1.0 op_sel_hi:[1,0]
	v_mul_f32_e32 v86, 0x3d372713, v82
	v_div_scale_f32 v88, s[0:1], v85, v85, 2.0
	v_mul_f32_e32 v87, 0x3d372713, v83
	v_div_scale_f32 v90, s[0:1], v84, v84, 2.0
	v_rcp_f32_e32 v92, v88
	v_mul_f32_e32 v86, v82, v86
	v_mul_f32_e32 v87, v83, v87
	v_rcp_f32_e32 v93, v90
	v_fma_f32 v86, v82, v86, v82
	v_fma_f32 v87, v83, v87, v83
	v_mul_f32_e32 v86, 0x3f4c422a, v86
	v_mul_f32_e32 v87, 0x3f4c422a, v87
	v_add_f32_e32 v86, v86, v86
	v_add_f32_e32 v87, v87, v87
	v_fma_f32 v95, -v88, v92, 1.0
	v_mul_f32_e32 v86, 0x3fb8aa3b, v86
	v_mul_f32_e32 v87, 0x3fb8aa3b, v87
	v_div_scale_f32 v89, vcc, 2.0, v85, 2.0
	v_fma_f32 v96, -v90, v93, 1.0
; DI unsigned pack2bf(float a, float b) { const f2_t v = {a, b}; return __builtin_bit_cast(unsigned, __builtin_convertvector(v, bf2_t)); }
; DI float gelu_t(float x) { float u = 0.7978845608028654f * (x + 0.044715f * x * x * x); float e = __expf(2.f * u); float t = 1.f - 2.f / (1.f + e); return 0.5f * x * (1.f + t); }
; DI void phase4(const Params& P, char* smem) {
;     ...
;       const int n = bcol + col0, i = n >> 4, h = n & 15, m = brow + row;
;       const float4 dsk = *reinterpret_cast<const float4*>(P.dsk + g * 16 + h);
;       const uint2 uu = *reinterpret_cast<const uint2*>(UG + ((long)g * 512 + m) * UGLD + n);
;       const float y0 = gelu_t(v[0] + dsk.x * __uint_as_float(uu.x << 16)), y1 = gelu_t(v[1] + dsk.y * __uint_as_float(uu.x & 0xffff0000u));
;       const float y2 = gelu_t(v[2] + dsk.z * __uint_as_float(uu.y << 16)), y3 = gelu_t(v[3] + dsk.w * __uint_as_float(uu.y & 0xffff0000u));
;       *reinterpret_cast<uint2*>(Yb + ((long)m * 64 + i) * 512 + g * 16 + h) = make_uint2(pack2bf(y0, y1), pack2bf(y2, y3));
	v_fmac_f32_e32 v92, v95, v92
	v_exp_f32_e32 v86, v86
	v_exp_f32_e32 v87, v87
	v_div_scale_f32 v91, s[0:1], 2.0, v84, 2.0
	v_fmac_f32_e32 v93, v96, v93
	v_mul_f32_e32 v95, v89, v92
	v_mul_f32_e32 v96, v91, v93
	v_fma_f32 v97, -v88, v95, v89
	v_fma_f32 v98, -v90, v96, v91
	v_fmac_f32_e32 v95, v97, v92
	v_fmac_f32_e32 v96, v98, v93
	v_fma_f32 v88, -v88, v95, v89
	v_pk_add_f32 v[86:87], v[86:87], 1.0 op_sel_hi:[1,0]
	v_fma_f32 v89, -v90, v96, v91
	v_div_fmas_f32 v88, v88, v92, v95
	s_mov_b64 vcc, s[0:1]
	v_div_scale_f32 v94, s[4:5], v87, v87, 2.0
	v_div_fixup_f32 v85, v88, v85, 2.0
	v_div_fmas_f32 v88, v89, v93, v96
	v_div_fixup_f32 v84, v88, v84, 2.0
	v_rcp_f32_e32 v88, v94
	v_pk_add_f32 v[84:85], v[84:85], 1.0 op_sel_hi:[1,0] neg_lo:[1,0] neg_hi:[1,0]
	v_pk_mul_f32 v[82:83], v[82:83], 0.5 op_sel_hi:[1,0]
	v_pk_add_f32 v[84:85], v[84:85], 1.0 op_sel_hi:[1,0]
	v_mfma_f32_16x16x32_bf16 v[28:31], v[56:59], v[12:15], v[28:31]
	v_mul_f32_e64 v80, v80, v84
	v_mul_f32_e64 v81, v81, v85
	v_fma_f32 v84, -v94, v88, 1.0
	v_fmac_f32_e32 v88, v84, v88
	v_div_scale_f32 v84, vcc, 2.0, v87, 2.0
	v_mul_f32_e32 v85, v84, v88
	v_fma_f32 v89, -v94, v85, v84
	v_fmac_f32_e32 v85, v89, v88
	v_div_scale_f32 v89, s[0:1], v86, v86, 2.0
	v_rcp_f32_e32 v90, v89
	v_fma_f32 v84, -v94, v85, v84
	v_div_fmas_f32 v84, v84, v88, v85
	v_div_fixup_f32 v85, v84, v87, 2.0
	v_fma_f32 v84, -v89, v90, 1.0
	v_fmac_f32_e32 v90, v84, v90
	v_div_scale_f32 v84, vcc, 2.0, v86, 2.0
	v_mul_f32_e32 v87, v84, v90
	v_fma_f32 v88, -v89, v87, v84
	v_fmac_f32_e32 v87, v88, v90
	v_fma_f32 v84, -v89, v87, v84
	v_div_fmas_f32 v84, v84, v90, v87
	v_div_fixup_f32 v84, v84, v86, 2.0
	v_pk_add_f32 v[84:85], v[84:85], 1.0 op_sel_hi:[1,0] neg_lo:[1,0] neg_hi:[1,0]
	v_cvt_pk_bf16_f32 v80, v80, v81
	v_pk_add_f32 v[84:85], v[84:85], 1.0 op_sel_hi:[1,0]
	v_or_b32_e32 v90, v205, v178
	v_pk_mul_f32 v[82:83], v[82:83], v[84:85]
	v_mfma_f32_16x16x32_bf16 v[28:31], v[60:63], v[20:23], v[28:31]
	v_cvt_pk_bf16_f32 v81, v82, v83
	v_lshl_add_u64 v[82:83], v[100:101], 0, v[104:105]
	v_lshl_add_u64 v[82:83], v[82:83], 0, v[152:153]
	v_lshl_add_u64 v[82:83], v[82:83], 0, v[146:147]
	global_store_dwordx2 v[82:83], v[80:81], off
	v_or_b32_e32 v80, v148, v90
	v_mad_u64_u32 v[80:81], s[0:1], v80, s9, v[154:155]
	v_mad_i32_i24 v81, v149, s9, v81
	v_lshl_add_u64 v[80:81], v[80:81], 0, v[126:127]
	v_mov_b32_e32 v86, v242
	v_mov_b32_e32 v87, v243
	v_mov_b32_e32 v82, v250
	v_mov_b32_e32 v83, v251
	v_mov_b32_e32 v84, v252
	v_mov_b32_e32 v85, v253
	v_mfma_f32_16x16x32_bf16 v[8:11], v[44:47], v[12:15], v[8:11]
	v_lshlrev_b32_e32 v88, 16, v86
	v_and_b32_e32 v89, 0xffff0000, v86
	v_pk_fma_f32 v[76:77], v[82:83], v[88:89], v[76:77]
	v_lshlrev_b32_e32 v86, 16, v87
	v_mul_f32_e32 v82, 0x3d372713, v76
	v_mul_f32_e32 v83, 0x3d372713, v77
	v_mul_f32_e32 v82, v76, v82
	v_mul_f32_e32 v83, v77, v83
	v_fma_f32 v82, v76, v82, v76
	v_fma_f32 v83, v77, v83, v77
	v_mul_f32_e32 v82, 0x3f4c422a, v82
	v_mul_f32_e32 v83, 0x3f4c422a, v83
	v_add_f32_e32 v82, v82, v82
	v_add_f32_e32 v83, v83, v83
	v_mul_f32_e32 v82, 0x3fb8aa3b, v82
	v_mul_f32_e32 v83, 0x3fb8aa3b, v83
	v_exp_f32_e32 v82, v82
	v_exp_f32_e32 v83, v83
	v_and_b32_e32 v87, 0xffff0000, v87
	v_pk_fma_f32 v[78:79], v[84:85], v[86:87], v[78:79]
	v_pk_mul_f32 v[76:77], v[76:77], 0.5 op_sel_hi:[1,0]
	v_pk_add_f32 v[82:83], v[82:83], 1.0 op_sel_hi:[1,0]
	v_mul_f32_e32 v84, 0x3d372713, v78
	v_div_scale_f32 v86, s[0:1], v83, v83, 2.0
	v_div_scale_f32 v88, s[0:1], v82, v82, 2.0
	v_rcp_f32_e32 v89, v86
	v_mul_f32_e32 v85, 0x3d372713, v79
	v_rcp_f32_e32 v91, v88
	v_mul_f32_e32 v84, v78, v84
	v_mul_f32_e32 v85, v79, v85
	v_fma_f32 v84, v78, v84, v78
	v_fma_f32 v85, v79, v85, v79
	v_mul_f32_e32 v84, 0x3f4c422a, v84
	v_mul_f32_e32 v85, 0x3f4c422a, v85
	v_fma_f32 v93, -v86, v89, 1.0
	v_add_f32_e32 v84, v84, v84
	v_add_f32_e32 v85, v85, v85
	v_div_scale_f32 v87, vcc, 2.0, v83, 2.0
	v_fma_f32 v94, -v88, v91, 1.0
	v_fmac_f32_e32 v89, v93, v89
	v_mul_f32_e32 v84, 0x3fb8aa3b, v84
	v_mul_f32_e32 v85, 0x3fb8aa3b, v85
	v_div_scale_f32 v92, s[0:1], 2.0, v82, 2.0
	v_fmac_f32_e32 v91, v94, v91
	v_mul_f32_e32 v93, v87, v89
	v_exp_f32_e32 v84, v84
	v_exp_f32_e32 v85, v85
	v_mul_f32_e32 v94, v92, v91
	v_fma_f32 v95, -v86, v93, v87
	v_fma_f32 v96, -v88, v94, v92
	v_fmac_f32_e32 v93, v95, v89
	v_fmac_f32_e32 v94, v96, v91
	v_fma_f32 v86, -v86, v93, v87
	v_fma_f32 v87, -v88, v94, v92
	v_div_fmas_f32 v86, v86, v89, v93
	s_mov_b64 vcc, s[0:1]
	v_pk_add_f32 v[84:85], v[84:85], 1.0 op_sel_hi:[1,0]
	v_div_fixup_f32 v83, v86, v83, 2.0
	v_div_fmas_f32 v86, v87, v91, v94
	v_div_fixup_f32 v82, v86, v82, 2.0
	v_div_scale_f32 v86, s[0:1], v85, v85, 2.0
	v_rcp_f32_e32 v87, v86
	v_pk_add_f32 v[82:83], v[82:83], 1.0 op_sel_hi:[1,0] neg_lo:[1,0] neg_hi:[1,0]
	v_pk_mul_f32 v[78:79], v[78:79], 0.5 op_sel_hi:[1,0]
	v_pk_add_f32 v[82:83], v[82:83], 1.0 op_sel_hi:[1,0]
	v_mfma_f32_16x16x32_bf16 v[8:11], v[48:51], v[20:23], v[8:11]
	v_mul_f32_e64 v76, v76, v82
	v_mul_f32_e64 v77, v77, v83
	v_fma_f32 v82, -v86, v87, 1.0
	v_fmac_f32_e32 v87, v82, v87
	v_div_scale_f32 v82, vcc, 2.0, v85, 2.0
	v_mul_f32_e32 v83, v82, v87
	v_fma_f32 v88, -v86, v83, v82
	v_fmac_f32_e32 v83, v88, v87
	v_fma_f32 v82, -v86, v83, v82
	v_div_scale_f32 v86, s[0:1], v84, v84, 2.0
	v_rcp_f32_e32 v88, v86
	v_div_fmas_f32 v82, v82, v87, v83
	v_div_fixup_f32 v83, v82, v85, 2.0
	v_mfma_f32_16x16x32_bf16 v[4:7], v[32:35], v[12:15], v[4:7]
	v_fma_f32 v82, -v86, v88, 1.0
	v_fmac_f32_e32 v88, v82, v88
	v_div_scale_f32 v82, vcc, 2.0, v84, 2.0
	v_mul_f32_e32 v85, v82, v88
	v_fma_f32 v87, -v86, v85, v82
	v_fmac_f32_e32 v85, v87, v88
	v_fma_f32 v82, -v86, v85, v82
	v_div_fmas_f32 v82, v82, v88, v85
; DI unsigned pack2bf(float a, float b) { const f2_t v = {a, b}; return __builtin_bit_cast(unsigned, __builtin_convertvector(v, bf2_t)); }
; DI float gelu_t(float x) { float u = 0.7978845608028654f * (x + 0.044715f * x * x * x); float e = __expf(2.f * u); float t = 1.f - 2.f / (1.f + e); return 0.5f * x * (1.f + t); }
; DI void phase4(const Params& P, char* smem) {
;     ...
;       const int n = bcol + col0, i = n >> 4, h = n & 15, m = brow + row;
;       const float4 dsk = *reinterpret_cast<const float4*>(P.dsk + g * 16 + h);
;       const uint2 uu = *reinterpret_cast<const uint2*>(UG + ((long)g * 512 + m) * UGLD + n);
;       const float y0 = gelu_t(v[0] + dsk.x * __uint_as_float(uu.x << 16)), y1 = gelu_t(v[1] + dsk.y * __uint_as_float(uu.x & 0xffff0000u));
;       const float y2 = gelu_t(v[2] + dsk.z * __uint_as_float(uu.y << 16)), y3 = gelu_t(v[3] + dsk.w * __uint_as_float(uu.y & 0xffff0000u));
;       *reinterpret_cast<uint2*>(Yb + ((long)m * 64 + i) * 512 + g * 16 + h) = make_uint2(pack2bf(y0, y1), pack2bf(y2, y3));
	v_div_fixup_f32 v82, v82, v84, 2.0
	v_pk_add_f32 v[82:83], v[82:83], 1.0 op_sel_hi:[1,0] neg_lo:[1,0] neg_hi:[1,0]
	v_mfma_f32_16x16x32_bf16 v[4:7], v[36:39], v[20:23], v[4:7]
	v_add_f32_e64 v82, v82, 1.0
	v_add_f32_e64 v83, v83, 1.0
	v_pk_mul_f32 v[78:79], v[78:79], v[82:83]
	v_cvt_pk_bf16_f32 v82, v76, v77
	v_lshlrev_b32_e32 v76, 16, v90
	v_mov_b32_e32 v77, v127
	v_lshl_add_u64 v[76:77], s[54:55], 0, v[76:77]
	v_cvt_pk_bf16_f32 v83, v78, v79
	v_lshl_add_u64 v[78:79], v[76:77], 0, v[156:157]
	v_lshl_add_u64 v[78:79], v[78:79], 0, v[152:153]
	v_lshl_add_u64 v[78:79], v[78:79], 0, v[146:147]
	global_store_dwordx2 v[78:79], v[82:83], off
	v_mov_b32_e32 v78, v244
	v_mov_b32_e32 v79, v245
	v_mfma_f32_16x16x32_bf16 v[0:3], v[16:19], v[12:15], v[0:3]
	v_mov_b32_e32 v82, v250
	v_mov_b32_e32 v83, v251
	v_mov_b32_e32 v84, v252
	v_mov_b32_e32 v85, v253
	v_lshlrev_b32_e32 v86, 16, v78
	v_and_b32_e32 v87, 0xffff0000, v78
	v_lshlrev_b32_e32 v78, 16, v79
	v_and_b32_e32 v79, 0xffff0000, v79
	v_pk_fma_f32 v[64:65], v[82:83], v[86:87], v[64:65]
	v_pk_fma_f32 v[66:67], v[84:85], v[78:79], v[66:67]
	v_mul_f32_e32 v78, 0x3d372713, v64
	v_mul_f32_e32 v79, 0x3d372713, v65
	v_mul_f32_e32 v78, v64, v78
	v_mul_f32_e32 v79, v65, v79
	v_fma_f32 v78, v64, v78, v64
	v_fma_f32 v79, v65, v79, v65
	v_mul_f32_e32 v78, 0x3f4c422a, v78
	v_mul_f32_e32 v79, 0x3f4c422a, v79
	v_add_f32_e32 v78, v78, v78
	v_add_f32_e32 v79, v79, v79
	v_mul_f32_e32 v78, 0x3fb8aa3b, v78
	v_mul_f32_e32 v79, 0x3fb8aa3b, v79
	v_exp_f32_e32 v78, v78
	v_exp_f32_e32 v79, v79
	v_mul_f32_e32 v82, 0x3d372713, v66
	v_mul_f32_e32 v83, 0x3d372713, v67
	v_mul_f32_e32 v82, v66, v82
	v_pk_add_f32 v[78:79], v[78:79], 1.0 op_sel_hi:[1,0]
	v_mul_f32_e32 v83, v67, v83
	v_div_scale_f32 v84, s[0:1], v79, v79, 2.0
	v_div_scale_f32 v86, s[0:1], v78, v78, 2.0
	v_rcp_f32_e32 v87, v84
	v_rcp_f32_e32 v88, v86
	v_fma_f32 v82, v66, v82, v66
	v_fma_f32 v83, v67, v83, v67
	v_mul_f32_e32 v82, 0x3f4c422a, v82
	v_mul_f32_e32 v83, 0x3f4c422a, v83
	v_fma_f32 v90, -v84, v87, 1.0
	v_add_f32_e32 v82, v82, v82
	v_add_f32_e32 v83, v83, v83
	v_div_scale_f32 v85, vcc, 2.0, v79, 2.0
	v_fma_f32 v91, -v86, v88, 1.0
	v_fmac_f32_e32 v87, v90, v87
	v_mul_f32_e32 v82, 0x3fb8aa3b, v82
	v_mul_f32_e32 v83, 0x3fb8aa3b, v83
	v_div_scale_f32 v89, s[0:1], 2.0, v78, 2.0
	v_fmac_f32_e32 v88, v91, v88
	v_mul_f32_e32 v90, v85, v87
	v_exp_f32_e32 v82, v82
	v_exp_f32_e32 v83, v83
	v_mul_f32_e32 v91, v89, v88
	v_fma_f32 v92, -v84, v90, v85
	v_fma_f32 v93, -v86, v91, v89
	v_fmac_f32_e32 v90, v92, v87
	v_fmac_f32_e32 v91, v93, v88
	v_fma_f32 v84, -v84, v90, v85
	v_fma_f32 v85, -v86, v91, v89
	v_div_fmas_f32 v84, v84, v87, v90
	s_mov_b64 vcc, s[0:1]
	v_pk_add_f32 v[82:83], v[82:83], 1.0 op_sel_hi:[1,0]
	v_div_fixup_f32 v79, v84, v79, 2.0
	v_div_fmas_f32 v84, v85, v88, v91
	v_div_fixup_f32 v78, v84, v78, 2.0
	v_div_scale_f32 v84, s[0:1], v83, v83, 2.0
	v_rcp_f32_e32 v85, v84
	v_pk_add_f32 v[78:79], v[78:79], 1.0 op_sel_hi:[1,0] neg_lo:[1,0] neg_hi:[1,0]
	v_pk_mul_f32 v[64:65], v[64:65], 0.5 op_sel_hi:[1,0]
	v_pk_add_f32 v[78:79], v[78:79], 1.0 op_sel_hi:[1,0]
	v_pk_mul_f32 v[66:67], v[66:67], 0.5 op_sel_hi:[1,0]
	v_pk_mul_f32 v[64:65], v[64:65], v[78:79]
	v_fma_f32 v78, -v84, v85, 1.0
	v_fmac_f32_e32 v85, v78, v85
	v_div_scale_f32 v78, vcc, 2.0, v83, 2.0
	v_mul_f32_e32 v79, v78, v85
	v_fma_f32 v86, -v84, v79, v78
	v_fmac_f32_e32 v79, v86, v85
	v_fma_f32 v78, -v84, v79, v78
	v_div_scale_f32 v84, s[0:1], v82, v82, 2.0
	v_rcp_f32_e32 v86, v84
	v_div_fmas_f32 v78, v78, v85, v79
	v_div_fixup_f32 v79, v78, v83, 2.0
	v_cvt_pk_bf16_f32 v64, v64, v65
	v_fma_f32 v78, -v84, v86, 1.0
	v_fmac_f32_e32 v86, v78, v86
	v_div_scale_f32 v78, vcc, 2.0, v82, 2.0
	v_mul_f32_e32 v83, v78, v86
	v_fma_f32 v85, -v84, v83, v78
	v_fmac_f32_e32 v83, v85, v86
	v_fma_f32 v78, -v84, v83, v78
	v_div_fmas_f32 v78, v78, v86, v83
	v_div_fixup_f32 v78, v78, v82, 2.0
	v_pk_add_f32 v[78:79], v[78:79], 1.0 op_sel_hi:[1,0] neg_lo:[1,0] neg_hi:[1,0]
	v_mfma_f32_16x16x32_bf16 v[0:3], v[24:27], v[20:23], v[0:3]
	v_add_f32_e64 v78, v78, 1.0
	v_add_f32_e64 v79, v79, 1.0
	v_pk_mul_f32 v[66:67], v[66:67], v[78:79]
	s_nop 0
	v_cvt_pk_bf16_f32 v65, v66, v67
	v_lshl_add_u64 v[66:67], v[76:77], 0, v[112:113]
	v_lshl_add_u64 v[66:67], v[66:67], 0, v[152:153]
	v_lshl_add_u64 v[66:67], v[66:67], 0, v[146:147]
	global_store_dwordx2 v[66:67], v[64:65], off
	v_mov_b32_e32 v78, v246
	v_mov_b32_e32 v79, v247
	v_lshlrev_b32_e32 v82, 16, v78
	v_mov_b32_e32 v64, v250
	v_mov_b32_e32 v65, v251
	v_mov_b32_e32 v66, v252
	v_mov_b32_e32 v67, v253
	v_and_b32_e32 v83, 0xffff0000, v78
	v_lshlrev_b32_e32 v78, 16, v79
	v_and_b32_e32 v79, 0xffff0000, v79
	v_pk_fma_f32 v[52:53], v[64:65], v[82:83], v[52:53]
	s_nop 0
	v_mul_f32_e32 v64, 0x3d372713, v52
	v_mul_f32_e32 v65, 0x3d372713, v53
	v_mul_f32_e32 v64, v52, v64
	v_mul_f32_e32 v65, v53, v65
	v_fma_f32 v64, v52, v64, v52
	v_fma_f32 v65, v53, v65, v53
	v_mul_f32_e32 v64, 0x3f4c422a, v64
	v_mul_f32_e32 v65, 0x3f4c422a, v65
	v_add_f32_e32 v64, v64, v64
	v_add_f32_e32 v65, v65, v65
	v_pk_fma_f32 v[54:55], v[66:67], v[78:79], v[54:55]
	v_mul_f32_e32 v64, 0x3fb8aa3b, v64
	v_mul_f32_e32 v65, 0x3fb8aa3b, v65
	v_mul_f32_e32 v66, 0x3d372713, v54
	v_mul_f32_e32 v67, 0x3d372713, v55
	v_exp_f32_e32 v64, v64
	v_exp_f32_e32 v65, v65
	v_mul_f32_e32 v66, v54, v66
	v_mul_f32_e32 v67, v55, v67
	v_fma_f32 v66, v54, v66, v54
	v_fma_f32 v67, v55, v67, v55
	v_mul_f32_e32 v66, 0x3f4c422a, v66
	v_mul_f32_e32 v67, 0x3f4c422a, v67
	v_add_f32_e32 v66, v66, v66
	v_add_f32_e32 v67, v67, v67
	v_pk_add_f32 v[64:65], v[64:65], 1.0 op_sel_hi:[1,0]
	v_mul_f32_e32 v66, 0x3fb8aa3b, v66
	v_mul_f32_e32 v67, 0x3fb8aa3b, v67
; DI unsigned pack2bf(float a, float b) { const f2_t v = {a, b}; return __builtin_bit_cast(unsigned, __builtin_convertvector(v, bf2_t)); }
; DI float gelu_t(float x) { float u = 0.7978845608028654f * (x + 0.044715f * x * x * x); float e = __expf(2.f * u); float t = 1.f - 2.f / (1.f + e); return 0.5f * x * (1.f + t); }
; DI void phase4(const Params& P, char* smem) {
;     ...
;       const int n = bcol + col0, i = n >> 4, h = n & 15, m = brow + row;
;       const float4 dsk = *reinterpret_cast<const float4*>(P.dsk + g * 16 + h);
;       const uint2 uu = *reinterpret_cast<const uint2*>(UG + ((long)g * 512 + m) * UGLD + n);
;       const float y0 = gelu_t(v[0] + dsk.x * __uint_as_float(uu.x << 16)), y1 = gelu_t(v[1] + dsk.y * __uint_as_float(uu.x & 0xffff0000u));
;       const float y2 = gelu_t(v[2] + dsk.z * __uint_as_float(uu.y << 16)), y3 = gelu_t(v[3] + dsk.w * __uint_as_float(uu.y & 0xffff0000u));
;       *reinterpret_cast<uint2*>(Yb + ((long)m * 64 + i) * 512 + g * 16 + h) = make_uint2(pack2bf(y0, y1), pack2bf(y2, y3));
	v_div_scale_f32 v78, s[0:1], v65, v65, 2.0
	v_exp_f32_e32 v66, v66
	v_exp_f32_e32 v67, v67
	v_div_scale_f32 v82, s[0:1], v64, v64, 2.0
	v_rcp_f32_e32 v84, v78
	v_rcp_f32_e32 v85, v82
	v_pk_add_f32 v[66:67], v[66:67], 1.0 op_sel_hi:[1,0]
	v_div_scale_f32 v79, vcc, 2.0, v65, 2.0
	v_fma_f32 v88, -v78, v84, 1.0
	v_div_scale_f32 v83, s[0:1], v67, v67, 2.0
	v_fma_f32 v89, -v82, v85, 1.0
	v_fmac_f32_e32 v84, v88, v84
	v_div_scale_f32 v87, s[0:1], 2.0, v64, 2.0
	v_fmac_f32_e32 v85, v89, v85
	v_mul_f32_e32 v88, v79, v84
	v_mul_f32_e32 v89, v87, v85
	v_fma_f32 v91, -v78, v88, v79
	v_fma_f32 v92, -v82, v89, v87
	v_fmac_f32_e32 v88, v91, v84
	v_fmac_f32_e32 v89, v92, v85
	v_fma_f32 v78, -v78, v88, v79
	v_rcp_f32_e32 v86, v83
	v_fma_f32 v79, -v82, v89, v87
	v_div_fmas_f32 v78, v78, v84, v88
	s_mov_b64 vcc, s[0:1]
	v_div_fixup_f32 v65, v78, v65, 2.0
	v_div_fmas_f32 v78, v79, v85, v89
	v_div_fixup_f32 v64, v78, v64, 2.0
	v_pk_add_f32 v[64:65], v[64:65], 1.0 op_sel_hi:[1,0] neg_lo:[1,0] neg_hi:[1,0]
	v_pk_mul_f32 v[52:53], v[52:53], 0.5 op_sel_hi:[1,0]
	v_fma_f32 v90, -v83, v86, 1.0
	v_pk_add_f32 v[64:65], v[64:65], 1.0 op_sel_hi:[1,0]
	v_fmac_f32_e32 v86, v90, v86
	v_pk_mul_f32 v[52:53], v[52:53], v[64:65]
	v_div_scale_f32 v64, vcc, 2.0, v67, 2.0
	v_mul_f32_e32 v65, v64, v86
	v_fma_f32 v78, -v83, v65, v64
	v_fmac_f32_e32 v65, v78, v86
	v_div_scale_f32 v78, s[0:1], v66, v66, 2.0
	v_rcp_f32_e32 v79, v78
	v_fma_f32 v64, -v83, v65, v64
	v_div_fmas_f32 v64, v64, v86, v65
	v_div_fixup_f32 v65, v64, v67, 2.0
	v_fma_f32 v64, -v78, v79, 1.0
	v_fmac_f32_e32 v79, v64, v79
	v_div_scale_f32 v64, vcc, 2.0, v66, 2.0
	v_mul_f32_e32 v67, v64, v79
	v_fma_f32 v82, -v78, v67, v64
	v_fmac_f32_e32 v67, v82, v79
	v_fma_f32 v64, -v78, v67, v64
	v_div_fmas_f32 v64, v64, v79, v67
	v_div_fixup_f32 v64, v64, v66, 2.0
	v_pk_add_f32 v[64:65], v[64:65], 1.0 op_sel_hi:[1,0] neg_lo:[1,0] neg_hi:[1,0]
	v_pk_mul_f32 v[54:55], v[54:55], 0.5 op_sel_hi:[1,0]
	v_pk_add_f32 v[64:65], v[64:65], 1.0 op_sel_hi:[1,0]
	v_cvt_pk_bf16_f32 v52, v52, v53
	v_pk_mul_f32 v[54:55], v[54:55], v[64:65]
	s_nop 0
	v_cvt_pk_bf16_f32 v53, v54, v55
	v_lshl_add_u64 v[54:55], v[76:77], 0, v[108:109]
	v_lshl_add_u64 v[54:55], v[54:55], 0, v[152:153]
	v_lshl_add_u64 v[54:55], v[54:55], 0, v[146:147]
	global_store_dwordx2 v[54:55], v[52:53], off
	v_mov_b32_e32 v64, v248
	v_mov_b32_e32 v65, v249
	v_lshlrev_b32_e32 v66, 16, v64
	v_mov_b32_e32 v52, v250
	v_mov_b32_e32 v53, v251
	v_mov_b32_e32 v54, v252
	v_mov_b32_e32 v55, v253
	v_and_b32_e32 v67, 0xffff0000, v64
	v_lshlrev_b32_e32 v64, 16, v65
	v_and_b32_e32 v65, 0xffff0000, v65
	v_pk_fma_f32 v[40:41], v[52:53], v[66:67], v[40:41]
	s_nop 0
	v_mul_f32_e32 v52, 0x3d372713, v40
	v_mul_f32_e32 v53, 0x3d372713, v41
	v_mul_f32_e32 v52, v40, v52
	v_mul_f32_e32 v53, v41, v53
	v_fma_f32 v52, v40, v52, v40
	v_fma_f32 v53, v41, v53, v41
	v_mul_f32_e32 v52, 0x3f4c422a, v52
	v_mul_f32_e32 v53, 0x3f4c422a, v53
	v_add_f32_e32 v52, v52, v52
	v_add_f32_e32 v53, v53, v53
	v_mul_f32_e32 v52, 0x3fb8aa3b, v52
	v_mul_f32_e32 v53, 0x3fb8aa3b, v53
	v_exp_f32_e32 v52, v52
	v_exp_f32_e32 v53, v53
	v_pk_fma_f32 v[42:43], v[54:55], v[64:65], v[42:43]
	v_pk_mul_f32 v[40:41], v[40:41], 0.5 op_sel_hi:[1,0]
	v_mul_f32_e32 v54, 0x3d372713, v42
	v_mul_f32_e32 v55, 0x3d372713, v43
	v_mul_f32_e32 v54, v42, v54
	v_mul_f32_e32 v55, v43, v55
	v_fma_f32 v54, v42, v54, v42
	v_fma_f32 v55, v43, v55, v43
	v_pk_add_f32 v[52:53], v[52:53], 1.0 op_sel_hi:[1,0]
	v_mul_f32_e32 v54, 0x3f4c422a, v54
	v_mul_f32_e32 v55, 0x3f4c422a, v55
	v_div_scale_f32 v64, s[0:1], v53, v53, 2.0
	v_add_f32_e32 v54, v54, v54
	v_add_f32_e32 v55, v55, v55
	v_div_scale_f32 v66, s[0:1], v52, v52, 2.0
	v_rcp_f32_e32 v69, v64
	v_mul_f32_e32 v54, 0x3fb8aa3b, v54
	v_mul_f32_e32 v55, 0x3fb8aa3b, v55
	v_rcp_f32_e32 v70, v66
	v_exp_f32_e32 v54, v54
	v_exp_f32_e32 v55, v55
	v_fma_f32 v73, -v64, v69, 1.0
	v_div_scale_f32 v65, vcc, 2.0, v53, 2.0
	v_fma_f32 v74, -v66, v70, 1.0
	v_fmac_f32_e32 v69, v73, v69
	v_pk_add_f32 v[54:55], v[54:55], 1.0 op_sel_hi:[1,0]
	v_div_scale_f32 v67, s[0:1], 2.0, v52, 2.0
	v_fmac_f32_e32 v70, v74, v70
	v_mul_f32_e32 v73, v65, v69
	v_div_scale_f32 v68, s[4:5], v55, v55, 2.0
	v_mul_f32_e32 v74, v67, v70
	v_fma_f32 v78, -v64, v73, v65
	v_rcp_f32_e32 v71, v68
	v_fma_f32 v79, -v66, v74, v67
	v_fmac_f32_e32 v73, v78, v69
	v_fmac_f32_e32 v74, v79, v70
	v_fma_f32 v64, -v64, v73, v65
	v_fma_f32 v65, -v66, v74, v67
	v_div_fmas_f32 v64, v64, v69, v73
	s_mov_b64 vcc, s[0:1]
	v_div_fixup_f32 v53, v64, v53, 2.0
	v_div_fmas_f32 v64, v65, v70, v74
	v_fma_f32 v75, -v68, v71, 1.0
	v_div_fixup_f32 v52, v64, v52, 2.0
	v_div_scale_f32 v72, s[4:5], 2.0, v55, 2.0
	v_fmac_f32_e32 v71, v75, v71
	v_pk_add_f32 v[52:53], v[52:53], 1.0 op_sel_hi:[1,0] neg_lo:[1,0] neg_hi:[1,0]
	v_mul_f32_e32 v75, v72, v71
	v_pk_add_f32 v[52:53], v[52:53], 1.0 op_sel_hi:[1,0]
	v_div_scale_f32 v64, s[0:1], v54, v54, 2.0
	v_pk_mul_f32 v[40:41], v[40:41], v[52:53]
	v_fma_f32 v52, -v68, v75, v72
	v_rcp_f32_e32 v65, v64
	v_fmac_f32_e32 v75, v52, v71
	v_fma_f32 v52, -v68, v75, v72
	s_mov_b64 vcc, s[4:5]
	v_div_fmas_f32 v52, v52, v71, v75
	v_div_fixup_f32 v53, v52, v55, 2.0
	v_fma_f32 v52, -v64, v65, 1.0
	v_fmac_f32_e32 v65, v52, v65
	v_div_scale_f32 v52, vcc, 2.0, v54, 2.0
	v_mul_f32_e32 v55, v52, v65
	v_fma_f32 v66, -v64, v55, v52
	v_fmac_f32_e32 v55, v66, v65
	v_fma_f32 v52, -v64, v55, v52
	v_div_fmas_f32 v52, v52, v65, v55
	v_div_fixup_f32 v52, v52, v54, 2.0
	v_pk_add_f32 v[52:53], v[52:53], 1.0 op_sel_hi:[1,0] neg_lo:[1,0] neg_hi:[1,0]
	v_pk_mul_f32 v[42:43], v[42:43], 0.5 op_sel_hi:[1,0]
	v_pk_add_f32 v[52:53], v[52:53], 1.0 op_sel_hi:[1,0]
	v_cvt_pk_bf16_f32 v40, v40, v41
	v_pk_mul_f32 v[42:43], v[42:43], v[52:53]
	v_or_b32_e32 v64, v205, v180
	v_cvt_pk_bf16_f32 v41, v42, v43
	v_lshl_add_u64 v[42:43], v[76:77], 0, v[104:105]
	v_lshl_add_u64 v[42:43], v[42:43], 0, v[152:153]
	v_lshl_add_u64 v[42:43], v[42:43], 0, v[146:147]
	global_store_dwordx2 v[42:43], v[40:41], off
	v_or_b32_e32 v40, v148, v64
	v_mad_u64_u32 v[40:41], s[0:1], v40, s9, v[154:155]
	v_mad_i32_i24 v41, v149, s9, v41
	v_lshl_add_u64 v[40:41], v[40:41], 0, v[126:127]
	s_waitcnt vmcnt(0)
; DI unsigned pack2bf(float a, float b) { const f2_t v = {a, b}; return __builtin_bit_cast(unsigned, __builtin_convertvector(v, bf2_t)); }
; DI float gelu_t(float x) { float u = 0.7978845608028654f * (x + 0.044715f * x * x * x); float e = __expf(2.f * u); float t = 1.f - 2.f / (1.f + e); return 0.5f * x * (1.f + t); }
; DI void phase4(const Params& P, char* smem) {
;     ...
;       const int n = bcol + col0, i = n >> 4, h = n & 15, m = brow + row;
;       const float4 dsk = *reinterpret_cast<const float4*>(P.dsk + g * 16 + h);
;       const uint2 uu = *reinterpret_cast<const uint2*>(UG + ((long)g * 512 + m) * UGLD + n);
;       const float y0 = gelu_t(v[0] + dsk.x * __uint_as_float(uu.x << 16)), y1 = gelu_t(v[1] + dsk.y * __uint_as_float(uu.x & 0xffff0000u));
;       const float y2 = gelu_t(v[2] + dsk.z * __uint_as_float(uu.y << 16)), y3 = gelu_t(v[3] + dsk.w * __uint_as_float(uu.y & 0xffff0000u));
;       *reinterpret_cast<uint2*>(Yb + ((long)m * 64 + i) * 512 + g * 16 + h) = make_uint2(pack2bf(y0, y1), pack2bf(y2, y3));
	v_mov_b32_e32 v42, v228
	v_mov_b32_e32 v43, v229
	v_mov_b32_e32 v52, v250
	v_mov_b32_e32 v53, v251
	v_mov_b32_e32 v54, v252
	v_mov_b32_e32 v55, v253
	v_lshlrev_b32_e32 v126, 16, v64
	v_lshlrev_b32_e32 v56, 16, v42
	v_and_b32_e32 v57, 0xffff0000, v42
	v_lshlrev_b32_e32 v42, 16, v43
	v_and_b32_e32 v43, 0xffff0000, v43
	v_pk_fma_f32 v[28:29], v[52:53], v[56:57], v[28:29]
	v_pk_fma_f32 v[30:31], v[54:55], v[42:43], v[30:31]
	v_mul_f32_e32 v42, 0x3d372713, v28
	v_mul_f32_e32 v43, 0x3d372713, v29
	v_mul_f32_e32 v42, v28, v42
	v_mul_f32_e32 v43, v29, v43
	v_mul_f32_e32 v52, 0x3d372713, v30
	v_mul_f32_e32 v53, 0x3d372713, v31
	v_fma_f32 v42, v28, v42, v28
	v_fma_f32 v43, v29, v43, v29
	v_mul_f32_e32 v52, v30, v52
	v_mul_f32_e32 v53, v31, v53
	v_mul_f32_e32 v42, 0x3f4c422a, v42
	v_mul_f32_e32 v43, 0x3f4c422a, v43
	v_fma_f32 v52, v30, v52, v30
	v_fma_f32 v53, v31, v53, v31
	v_add_f32_e32 v42, v42, v42
	v_add_f32_e32 v43, v43, v43
	v_mul_f32_e32 v52, 0x3f4c422a, v52
	v_mul_f32_e32 v53, 0x3f4c422a, v53
	v_mul_f32_e32 v42, 0x3fb8aa3b, v42
	v_mul_f32_e32 v43, 0x3fb8aa3b, v43
	v_add_f32_e32 v52, v52, v52
	v_add_f32_e32 v53, v53, v53
	v_exp_f32_e32 v42, v42
	v_exp_f32_e32 v43, v43
	v_mul_f32_e32 v52, 0x3fb8aa3b, v52
	v_mul_f32_e32 v53, 0x3fb8aa3b, v53
	v_exp_f32_e32 v52, v52
	v_exp_f32_e32 v53, v53
	v_pk_add_f32 v[42:43], v[42:43], 1.0 op_sel_hi:[1,0]
	v_pk_mul_f32 v[28:29], v[28:29], 0.5 op_sel_hi:[1,0]
	v_div_scale_f32 v54, s[0:1], v43, v43, 2.0
	v_pk_add_f32 v[52:53], v[52:53], 1.0 op_sel_hi:[1,0]
	v_div_scale_f32 v56, s[0:1], v42, v42, 2.0
	v_rcp_f32_e32 v58, v54
	v_div_scale_f32 v57, s[0:1], v53, v53, 2.0
	v_rcp_f32_e32 v59, v56
	v_rcp_f32_e32 v60, v57
	v_fma_f32 v62, -v54, v58, 1.0
	v_div_scale_f32 v55, vcc, 2.0, v43, 2.0
	v_fma_f32 v63, -v56, v59, 1.0
	v_fmac_f32_e32 v58, v62, v58
	v_div_scale_f32 v61, s[0:1], 2.0, v42, 2.0
	v_fma_f32 v65, -v57, v60, 1.0
	v_fmac_f32_e32 v59, v63, v59
	v_mul_f32_e32 v62, v55, v58
	v_fmac_f32_e32 v60, v65, v60
	v_mul_f32_e32 v63, v61, v59
	v_fma_f32 v65, -v54, v62, v55
	v_fma_f32 v66, -v56, v63, v61
	v_fmac_f32_e32 v62, v65, v58
	v_fmac_f32_e32 v63, v66, v59
	v_fma_f32 v54, -v54, v62, v55
	v_fma_f32 v55, -v56, v63, v61
	v_div_fmas_f32 v54, v54, v58, v62
	s_mov_b64 vcc, s[0:1]
	v_div_fixup_f32 v43, v54, v43, 2.0
	v_div_fmas_f32 v54, v55, v59, v63
	v_div_fixup_f32 v42, v54, v42, 2.0
	v_pk_add_f32 v[42:43], v[42:43], 1.0 op_sel_hi:[1,0] neg_lo:[1,0] neg_hi:[1,0]
	v_pk_mul_f32 v[30:31], v[30:31], 0.5 op_sel_hi:[1,0]
	v_pk_add_f32 v[42:43], v[42:43], 1.0 op_sel_hi:[1,0]
	s_nop 0
	v_pk_mul_f32 v[28:29], v[28:29], v[42:43]
	v_div_scale_f32 v42, vcc, 2.0, v53, 2.0
	v_mul_f32_e32 v43, v42, v60
	v_fma_f32 v54, -v57, v43, v42
	v_fmac_f32_e32 v43, v54, v60
	v_div_scale_f32 v54, s[0:1], v52, v52, 2.0
	v_rcp_f32_e32 v55, v54
	v_fma_f32 v42, -v57, v43, v42
	v_div_fmas_f32 v42, v42, v60, v43
	v_div_fixup_f32 v43, v42, v53, 2.0
	v_fma_f32 v42, -v54, v55, 1.0
	v_fmac_f32_e32 v55, v42, v55
	v_div_scale_f32 v42, vcc, 2.0, v52, 2.0
	v_mul_f32_e32 v53, v42, v55
	v_fma_f32 v56, -v54, v53, v42
	v_fmac_f32_e32 v53, v56, v55
	v_fma_f32 v42, -v54, v53, v42
	v_div_fmas_f32 v42, v42, v55, v53
	v_div_fixup_f32 v42, v42, v52, 2.0
	v_pk_add_f32 v[42:43], v[42:43], 1.0 op_sel_hi:[1,0] neg_lo:[1,0] neg_hi:[1,0]
	s_nop 0
	v_pk_add_f32 v[42:43], v[42:43], 1.0 op_sel_hi:[1,0]
	s_nop 0
	v_pk_mul_f32 v[30:31], v[30:31], v[42:43]
	v_cvt_pk_bf16_f32 v42, v28, v29
	v_lshl_add_u64 v[28:29], s[54:55], 0, v[126:127]
	v_cvt_pk_bf16_f32 v43, v30, v31
	v_lshl_add_u64 v[30:31], v[28:29], 0, v[156:157]
	v_lshl_add_u64 v[30:31], v[30:31], 0, v[152:153]
	v_lshl_add_u64 v[30:31], v[30:31], 0, v[146:147]
	global_store_dwordx2 v[30:31], v[42:43], off
	v_mov_b32_e32 v30, v230
	v_mov_b32_e32 v31, v231
	v_lshlrev_b32_e32 v46, 16, v30
	v_mov_b32_e32 v42, v250
	v_mov_b32_e32 v43, v251
	v_mov_b32_e32 v44, v252
	v_mov_b32_e32 v45, v253
	v_and_b32_e32 v47, 0xffff0000, v30
	v_lshlrev_b32_e32 v30, 16, v31
	v_and_b32_e32 v31, 0xffff0000, v31
	v_pk_fma_f32 v[8:9], v[42:43], v[46:47], v[8:9]
	v_pk_fma_f32 v[10:11], v[44:45], v[30:31], v[10:11]
	v_mul_f32_e32 v30, 0x3d372713, v8
	v_mul_f32_e32 v31, 0x3d372713, v9
	v_mul_f32_e32 v30, v8, v30
	v_mul_f32_e32 v31, v9, v31
	v_fma_f32 v30, v8, v30, v8
	v_fma_f32 v31, v9, v31, v9
	v_mul_f32_e32 v30, 0x3f4c422a, v30
	v_mul_f32_e32 v31, 0x3f4c422a, v31
	v_add_f32_e32 v30, v30, v30
	v_add_f32_e32 v31, v31, v31
	v_mul_f32_e32 v30, 0x3fb8aa3b, v30
	v_mul_f32_e32 v31, 0x3fb8aa3b, v31
	v_exp_f32_e32 v30, v30
	v_exp_f32_e32 v31, v31
	v_mul_f32_e32 v42, 0x3d372713, v10
	v_mul_f32_e32 v43, 0x3d372713, v11
	v_mul_f32_e32 v42, v10, v42
	v_mul_f32_e32 v43, v11, v43
	v_fma_f32 v42, v10, v42, v10
	v_fma_f32 v43, v11, v43, v11
	v_pk_add_f32 v[30:31], v[30:31], 1.0 op_sel_hi:[1,0]
	v_mul_f32_e32 v42, 0x3f4c422a, v42
	v_mul_f32_e32 v43, 0x3f4c422a, v43
	v_div_scale_f32 v44, s[0:1], v31, v31, 2.0
	v_add_f32_e32 v42, v42, v42
	v_add_f32_e32 v43, v43, v43
	v_div_scale_f32 v46, s[0:1], v30, v30, 2.0
	v_rcp_f32_e32 v49, v44
	v_mul_f32_e32 v42, 0x3fb8aa3b, v42
	v_mul_f32_e32 v43, 0x3fb8aa3b, v43
	v_rcp_f32_e32 v50, v46
	v_exp_f32_e32 v42, v42
	v_exp_f32_e32 v43, v43
	v_fma_f32 v53, -v44, v49, 1.0
	v_div_scale_f32 v45, vcc, 2.0, v31, 2.0
	v_fma_f32 v54, -v46, v50, 1.0
	v_fmac_f32_e32 v49, v53, v49
	v_pk_add_f32 v[42:43], v[42:43], 1.0 op_sel_hi:[1,0]
	v_div_scale_f32 v47, s[0:1], 2.0, v30, 2.0
	v_fmac_f32_e32 v50, v54, v50
	v_mul_f32_e32 v53, v45, v49
	v_div_scale_f32 v48, s[4:5], v43, v43, 2.0
	v_mul_f32_e32 v54, v47, v50
	v_fma_f32 v56, -v44, v53, v45
	v_rcp_f32_e32 v51, v48
	v_fma_f32 v57, -v46, v54, v47
	v_fmac_f32_e32 v53, v56, v49
	v_fmac_f32_e32 v54, v57, v50
; DI unsigned pack2bf(float a, float b) { const f2_t v = {a, b}; return __builtin_bit_cast(unsigned, __builtin_convertvector(v, bf2_t)); }
; DI float gelu_t(float x) { float u = 0.7978845608028654f * (x + 0.044715f * x * x * x); float e = __expf(2.f * u); float t = 1.f - 2.f / (1.f + e); return 0.5f * x * (1.f + t); }
; DI void phase4(const Params& P, char* smem) {
;     ...
;       const int n = bcol + col0, i = n >> 4, h = n & 15, m = brow + row;
;       const float4 dsk = *reinterpret_cast<const float4*>(P.dsk + g * 16 + h);
;       const uint2 uu = *reinterpret_cast<const uint2*>(UG + ((long)g * 512 + m) * UGLD + n);
;       const float y0 = gelu_t(v[0] + dsk.x * __uint_as_float(uu.x << 16)), y1 = gelu_t(v[1] + dsk.y * __uint_as_float(uu.x & 0xffff0000u));
;       const float y2 = gelu_t(v[2] + dsk.z * __uint_as_float(uu.y << 16)), y3 = gelu_t(v[3] + dsk.w * __uint_as_float(uu.y & 0xffff0000u));
;       *reinterpret_cast<uint2*>(Yb + ((long)m * 64 + i) * 512 + g * 16 + h) = make_uint2(pack2bf(y0, y1), pack2bf(y2, y3));
	v_fma_f32 v44, -v44, v53, v45
	v_fma_f32 v45, -v46, v54, v47
	v_div_fmas_f32 v44, v44, v49, v53
	s_mov_b64 vcc, s[0:1]
	v_div_fixup_f32 v31, v44, v31, 2.0
	v_div_fmas_f32 v44, v45, v50, v54
	v_fma_f32 v55, -v48, v51, 1.0
	v_div_fixup_f32 v30, v44, v30, 2.0
	v_div_scale_f32 v52, s[4:5], 2.0, v43, 2.0
	v_fmac_f32_e32 v51, v55, v51
	v_pk_add_f32 v[30:31], v[30:31], 1.0 op_sel_hi:[1,0] neg_lo:[1,0] neg_hi:[1,0]
	v_pk_mul_f32 v[8:9], v[8:9], 0.5 op_sel_hi:[1,0]
	v_mul_f32_e32 v55, v52, v51
	v_pk_add_f32 v[30:31], v[30:31], 1.0 op_sel_hi:[1,0]
	v_div_scale_f32 v44, s[0:1], v42, v42, 2.0
	v_pk_mul_f32 v[8:9], v[8:9], v[30:31]
	v_fma_f32 v30, -v48, v55, v52
	v_rcp_f32_e32 v45, v44
	v_fmac_f32_e32 v55, v30, v51
	v_fma_f32 v30, -v48, v55, v52
	s_mov_b64 vcc, s[4:5]
	v_div_fmas_f32 v30, v30, v51, v55
	v_div_fixup_f32 v31, v30, v43, 2.0
	v_fma_f32 v30, -v44, v45, 1.0
	v_fmac_f32_e32 v45, v30, v45
	v_div_scale_f32 v30, vcc, 2.0, v42, 2.0
	v_mul_f32_e32 v43, v30, v45
	v_fma_f32 v46, -v44, v43, v30
	v_fmac_f32_e32 v43, v46, v45
	v_fma_f32 v30, -v44, v43, v30
	v_div_fmas_f32 v30, v30, v45, v43
	v_div_fixup_f32 v30, v30, v42, 2.0
	v_pk_add_f32 v[30:31], v[30:31], 1.0 op_sel_hi:[1,0] neg_lo:[1,0] neg_hi:[1,0]
	v_pk_mul_f32 v[10:11], v[10:11], 0.5 op_sel_hi:[1,0]
	v_pk_add_f32 v[30:31], v[30:31], 1.0 op_sel_hi:[1,0]
	v_cvt_pk_bf16_f32 v8, v8, v9
	v_pk_mul_f32 v[10:11], v[10:11], v[30:31]
	s_nop 0
	v_cvt_pk_bf16_f32 v9, v10, v11
	v_lshl_add_u64 v[10:11], v[28:29], 0, v[112:113]
	v_lshl_add_u64 v[10:11], v[10:11], 0, v[152:153]
	v_lshl_add_u64 v[10:11], v[10:11], 0, v[146:147]
	global_store_dwordx2 v[10:11], v[8:9], off
	v_mov_b32_e32 v30, v232
	v_mov_b32_e32 v31, v233
	v_lshlrev_b32_e32 v32, 16, v30
	v_mov_b32_e32 v8, v250
	v_mov_b32_e32 v9, v251
	v_mov_b32_e32 v10, v252
	v_mov_b32_e32 v11, v253
	v_and_b32_e32 v33, 0xffff0000, v30
	v_lshlrev_b32_e32 v30, 16, v31
	v_and_b32_e32 v31, 0xffff0000, v31
	v_pk_fma_f32 v[4:5], v[8:9], v[32:33], v[4:5]
	s_nop 0
	v_mul_f32_e32 v8, 0x3d372713, v4
	v_mul_f32_e32 v9, 0x3d372713, v5
	v_mul_f32_e32 v8, v4, v8
	v_mul_f32_e32 v9, v5, v9
	v_fma_f32 v8, v4, v8, v4
	v_fma_f32 v9, v5, v9, v5
	v_mul_f32_e32 v8, 0x3f4c422a, v8
	v_mul_f32_e32 v9, 0x3f4c422a, v9
	v_add_f32_e32 v8, v8, v8
	v_add_f32_e32 v9, v9, v9
	v_mul_f32_e32 v8, 0x3fb8aa3b, v8
	v_mul_f32_e32 v9, 0x3fb8aa3b, v9
	v_exp_f32_e32 v8, v8
	v_exp_f32_e32 v9, v9
	v_pk_fma_f32 v[6:7], v[10:11], v[30:31], v[6:7]
	v_pk_mul_f32 v[4:5], v[4:5], 0.5 op_sel_hi:[1,0]
	v_mul_f32_e32 v10, 0x3d372713, v6
	v_mul_f32_e32 v11, 0x3d372713, v7
	v_mul_f32_e32 v10, v6, v10
	v_mul_f32_e32 v11, v7, v11
	v_pk_add_f32 v[8:9], v[8:9], 1.0 op_sel_hi:[1,0]
	v_fma_f32 v10, v6, v10, v6
	v_fma_f32 v11, v7, v11, v7
	v_div_scale_f32 v30, s[0:1], v9, v9, 2.0
	v_mul_f32_e32 v10, 0x3f4c422a, v10
	v_mul_f32_e32 v11, 0x3f4c422a, v11
	v_div_scale_f32 v32, s[0:1], v8, v8, 2.0
	v_rcp_f32_e32 v35, v30
	v_add_f32_e32 v10, v10, v10
	v_add_f32_e32 v11, v11, v11
	v_rcp_f32_e32 v36, v32
	v_mul_f32_e32 v10, 0x3fb8aa3b, v10
	v_mul_f32_e32 v11, 0x3fb8aa3b, v11
	v_exp_f32_e32 v10, v10
	v_exp_f32_e32 v11, v11
	v_fma_f32 v39, -v30, v35, 1.0
	v_div_scale_f32 v31, vcc, 2.0, v9, 2.0
	v_fma_f32 v42, -v32, v36, 1.0
	v_fmac_f32_e32 v35, v39, v35
	v_div_scale_f32 v33, s[0:1], 2.0, v8, 2.0
	v_fmac_f32_e32 v36, v42, v36
	v_mul_f32_e32 v39, v31, v35
	v_pk_add_f32 v[10:11], v[10:11], 1.0 op_sel_hi:[1,0]
	v_mul_f32_e32 v42, v33, v36
	v_fma_f32 v44, -v30, v39, v31
	v_div_scale_f32 v34, s[4:5], v11, v11, 2.0
	v_fma_f32 v45, -v32, v42, v33
	v_fmac_f32_e32 v39, v44, v35
	v_rcp_f32_e32 v37, v34
	v_fmac_f32_e32 v42, v45, v36
	v_fma_f32 v30, -v30, v39, v31
	v_fma_f32 v31, -v32, v42, v33
	v_div_fmas_f32 v30, v30, v35, v39
	s_mov_b64 vcc, s[0:1]
	v_div_fixup_f32 v9, v30, v9, 2.0
	v_div_fmas_f32 v30, v31, v36, v42
	v_div_fixup_f32 v8, v30, v8, 2.0
	v_fma_f32 v43, -v34, v37, 1.0
	v_pk_add_f32 v[8:9], v[8:9], 1.0 op_sel_hi:[1,0] neg_lo:[1,0] neg_hi:[1,0]
	v_div_scale_f32 v38, s[4:5], 2.0, v11, 2.0
	v_fmac_f32_e32 v37, v43, v37
	v_pk_add_f32 v[8:9], v[8:9], 1.0 op_sel_hi:[1,0]
	v_mul_f32_e32 v43, v38, v37
	v_pk_mul_f32 v[4:5], v[4:5], v[8:9]
	v_div_scale_f32 v8, s[0:1], v10, v10, 2.0
	v_fma_f32 v46, -v34, v43, v38
	v_rcp_f32_e32 v30, v8
	v_fmac_f32_e32 v43, v46, v37
	v_fma_f32 v32, -v34, v43, v38
; DI unsigned pack2bf(float a, float b) { const f2_t v = {a, b}; return __builtin_bit_cast(unsigned, __builtin_convertvector(v, bf2_t)); }
; DI float gelu_t(float x) { float u = 0.7978845608028654f * (x + 0.044715f * x * x * x); float e = __expf(2.f * u); float t = 1.f - 2.f / (1.f + e); return 0.5f * x * (1.f + t); }
; #define TILE_LOOP(tile, N, C)                                                                                          \
;   for (int q0_ = (RBLK >> 3) * 2, tile = 0;                                                                            \
;        q0_ < (N) / 8 && ((tile = xcd_tile((q0_ + VHALF < (N) / 8 ? q0_ + VHALF : q0_), RBLK & 7, (C))), true);          \
;        q0_ += (RGRID >> 3) * 2)
; DI void phase4(const Params& P, char* smem) {
;     ...
;   TILE_LOOP(tile, 32 * 4 * 8, 8) {
;     const int trow = tile >> 3, g = (trow >> 5) * 8 + (tile & 7), brow = (trow & 3) * 128, cidx = (trow >> 2) & 7, bcol = ((trow & 64) ? 7 - cidx : cidx) * 128;
;     gemm_tile<true>(UG + ((long)g * 512 + brow) * UGLD, UGLD, Wy + ((long)g * 1024 + bcol) * UGLD, UGLD, 0, (bcol + 128) / 64, 16, 18, smem, [&](int row, int col0, f32x4 v) {
;       const int n = bcol + col0, i = n >> 4, h = n & 15, m = brow + row;
;       const float4 dsk = *reinterpret_cast<const float4*>(P.dsk + g * 16 + h);
;       const uint2 uu = *reinterpret_cast<const uint2*>(UG + ((long)g * 512 + m) * UGLD + n);
;       const float y0 = gelu_t(v[0] + dsk.x * __uint_as_float(uu.x << 16)), y1 = gelu_t(v[1] + dsk.y * __uint_as_float(uu.x & 0xffff0000u));
;       const float y2 = gelu_t(v[2] + dsk.z * __uint_as_float(uu.y << 16)), y3 = gelu_t(v[3] + dsk.w * __uint_as_float(uu.y & 0xffff0000u));
;       *reinterpret_cast<uint2*>(Yb + ((long)m * 64 + i) * 512 + g * 16 + h) = make_uint2(pack2bf(y0, y1), pack2bf(y2, y3));
;     });
	s_mov_b64 vcc, s[4:5]
	v_div_fmas_f32 v9, v32, v37, v43
	v_div_fixup_f32 v9, v9, v11, 2.0
	v_fma_f32 v11, -v8, v30, 1.0
	v_fmac_f32_e32 v30, v11, v30
	v_div_scale_f32 v11, vcc, 2.0, v10, 2.0
	v_mul_f32_e32 v31, v11, v30
	v_fma_f32 v32, -v8, v31, v11
	v_fmac_f32_e32 v31, v32, v30
	v_fma_f32 v8, -v8, v31, v11
	v_div_fmas_f32 v8, v8, v30, v31
	v_div_fixup_f32 v8, v8, v10, 2.0
	v_pk_add_f32 v[8:9], v[8:9], 1.0 op_sel_hi:[1,0] neg_lo:[1,0] neg_hi:[1,0]
	v_pk_mul_f32 v[6:7], v[6:7], 0.5 op_sel_hi:[1,0]
	v_pk_add_f32 v[8:9], v[8:9], 1.0 op_sel_hi:[1,0]
	v_cvt_pk_bf16_f32 v4, v4, v5
	v_pk_mul_f32 v[6:7], v[6:7], v[8:9]
	s_nop 0
	v_cvt_pk_bf16_f32 v5, v6, v7
	v_lshl_add_u64 v[6:7], v[28:29], 0, v[108:109]
	v_lshl_add_u64 v[6:7], v[6:7], 0, v[152:153]
	v_lshl_add_u64 v[6:7], v[6:7], 0, v[146:147]
	global_store_dwordx2 v[6:7], v[4:5], off
	v_mov_b32_e32 v8, v226
	v_mov_b32_e32 v9, v227
	v_lshlrev_b32_e32 v10, 16, v8
	v_mov_b32_e32 v4, v250
	v_mov_b32_e32 v5, v251
	v_mov_b32_e32 v6, v252
	v_mov_b32_e32 v7, v253
	v_and_b32_e32 v11, 0xffff0000, v8
	v_lshlrev_b32_e32 v8, 16, v9
	v_and_b32_e32 v9, 0xffff0000, v9
	v_pk_fma_f32 v[0:1], v[4:5], v[10:11], v[0:1]
	s_nop 0
	v_mul_f32_e32 v4, 0x3d372713, v0
	v_mul_f32_e32 v5, 0x3d372713, v1
	v_mul_f32_e32 v4, v0, v4
	v_mul_f32_e32 v5, v1, v5
	v_fma_f32 v4, v0, v4, v0
	v_fma_f32 v5, v1, v5, v1
	v_mul_f32_e32 v4, 0x3f4c422a, v4
	v_mul_f32_e32 v5, 0x3f4c422a, v5
	v_add_f32_e32 v4, v4, v4
	v_add_f32_e32 v5, v5, v5
	v_pk_fma_f32 v[2:3], v[6:7], v[8:9], v[2:3]
	v_mul_f32_e32 v4, 0x3fb8aa3b, v4
	v_mul_f32_e32 v5, 0x3fb8aa3b, v5
	v_mul_f32_e32 v6, 0x3d372713, v2
	v_mul_f32_e32 v7, 0x3d372713, v3
	v_exp_f32_e32 v4, v4
	v_exp_f32_e32 v5, v5
	v_mul_f32_e32 v6, v2, v6
	v_mul_f32_e32 v7, v3, v7
	v_fma_f32 v6, v2, v6, v2
	v_fma_f32 v7, v3, v7, v3
	v_mul_f32_e32 v6, 0x3f4c422a, v6
	v_mul_f32_e32 v7, 0x3f4c422a, v7
	v_add_f32_e32 v6, v6, v6
	v_add_f32_e32 v7, v7, v7
	v_pk_add_f32 v[4:5], v[4:5], 1.0 op_sel_hi:[1,0]
	v_mul_f32_e32 v6, 0x3fb8aa3b, v6
	v_mul_f32_e32 v7, 0x3fb8aa3b, v7
	v_div_scale_f32 v8, s[0:1], v5, v5, 2.0
	v_exp_f32_e32 v6, v6
	v_exp_f32_e32 v7, v7
	v_div_scale_f32 v10, s[0:1], v4, v4, 2.0
	v_rcp_f32_e32 v15, v8
	v_rcp_f32_e32 v16, v10
	v_pk_add_f32 v[6:7], v[6:7], 1.0 op_sel_hi:[1,0]
	v_div_scale_f32 v9, vcc, 2.0, v5, 2.0
	v_fma_f32 v19, -v8, v15, 1.0
	v_div_scale_f32 v12, s[4:5], v7, v7, 2.0
	v_fma_f32 v20, -v10, v16, 1.0
	v_fmac_f32_e32 v15, v19, v15
	v_div_scale_f32 v11, s[0:1], 2.0, v4, 2.0
	v_rcp_f32_e32 v17, v12
	v_fmac_f32_e32 v16, v20, v16
	v_mul_f32_e32 v19, v9, v15
	v_mul_f32_e32 v20, v11, v16
	v_fma_f32 v22, -v8, v19, v9
	v_fma_f32 v23, -v10, v20, v11
	v_fmac_f32_e32 v19, v22, v15
	v_fmac_f32_e32 v20, v23, v16
	v_fma_f32 v8, -v8, v19, v9
	v_div_scale_f32 v14, s[12:13], v6, v6, 2.0
	v_fma_f32 v21, -v12, v17, 1.0
	v_fma_f32 v9, -v10, v20, v11
	v_div_fmas_f32 v8, v8, v15, v19
	s_mov_b64 vcc, s[0:1]
	v_div_scale_f32 v13, s[4:5], 2.0, v7, 2.0
	v_rcp_f32_e32 v18, v14
	v_fmac_f32_e32 v17, v21, v17
	v_div_fixup_f32 v5, v8, v5, 2.0
	v_div_fmas_f32 v8, v9, v16, v20
	v_mul_f32_e32 v21, v13, v17
	v_div_fixup_f32 v4, v8, v4, 2.0
	v_fma_f32 v24, -v12, v21, v13
	v_pk_add_f32 v[4:5], v[4:5], 1.0 op_sel_hi:[1,0] neg_lo:[1,0] neg_hi:[1,0]
	v_pk_mul_f32 v[0:1], v[0:1], 0.5 op_sel_hi:[1,0]
	v_fmac_f32_e32 v21, v24, v17
	v_pk_add_f32 v[4:5], v[4:5], 1.0 op_sel_hi:[1,0]
	v_fma_f32 v10, -v12, v21, v13
	s_mov_b64 vcc, s[4:5]
	v_pk_mul_f32 v[0:1], v[0:1], v[4:5]
	v_fma_f32 v4, -v14, v18, 1.0
	v_div_fmas_f32 v8, v10, v17, v21
	v_fmac_f32_e32 v18, v4, v18
	v_div_scale_f32 v4, vcc, 2.0, v6, 2.0
	v_div_fixup_f32 v5, v8, v7, 2.0
	v_mul_f32_e32 v7, v4, v18
	v_fma_f32 v8, -v14, v7, v4
	v_fmac_f32_e32 v7, v8, v18
	v_fma_f32 v4, -v14, v7, v4
	v_div_fmas_f32 v4, v4, v18, v7
	v_div_fixup_f32 v4, v4, v6, 2.0
	v_pk_add_f32 v[4:5], v[4:5], 1.0 op_sel_hi:[1,0] neg_lo:[1,0] neg_hi:[1,0]
	v_pk_mul_f32 v[2:3], v[2:3], 0.5 op_sel_hi:[1,0]
	v_pk_add_f32 v[4:5], v[4:5], 1.0 op_sel_hi:[1,0]
	v_cvt_pk_bf16_f32 v0, v0, v1
	v_pk_mul_f32 v[2:3], v[2:3], v[4:5]
	s_nop 0
	v_cvt_pk_bf16_f32 v1, v2, v3
	v_lshl_add_u64 v[2:3], v[28:29], 0, v[104:105]
	v_lshl_add_u64 v[2:3], v[2:3], 0, v[152:153]
	v_lshl_add_u64 v[2:3], v[2:3], 0, v[146:147]
	global_store_dwordx2 v[2:3], v[0:1], off
	s_cbranch_scc1 .LBB0_754
